# on top of setprio removal: dropped the redundant post-barrier lgkmcnt(0) before each MFMA block in all K-loops; P0 row split 11/21
# baseline (speedup 1.0000x reference)
.LBB0_256:
	v_add_u32_e32 v172, s70, v160
	v_add_u32_e32 v188, s71, v160
	ds_read_b128 v[154:157], v172
	ds_read_b128 v[164:167], v172 offset:1024
	ds_read_b128 v[168:171], v172 offset:2048
	ds_read_b128 v[172:175], v172 offset:3072
	ds_read_b128 v[176:179], v188
	ds_read_b128 v[180:183], v188 offset:1024
	ds_read_b128 v[184:187], v188 offset:2048
	ds_read_b128 v[188:191], v188 offset:3072
	s_add_i32 s75, s30, 2
	s_add_u32 s31, s28, 0xfffc0080
	s_addc_u32 s34, s29, -1
	s_cmp_eq_u32 s67, s30
	s_cselect_b32 s30, s26, s17
	s_cselect_b32 s35, s25, s34
	s_cselect_b32 s34, s24, s31
	s_cselect_b32 s31, s27, s19
	v_lshl_add_u64 v[224:225], s[28:29], 0, v[146:147]
	s_add_i32 m0, s58, 0xc000
	ds_read_b128 v[192:195], v163
	ds_read_b128 v[196:199], v163 offset:1024
	ds_read_b128 v[200:203], v163 offset:2048
	ds_read_b128 v[204:207], v163 offset:3072
	ds_read_b128 v[208:211], v163 offset:4096
	ds_read_b128 v[212:215], v163 offset:5120
	ds_read_b128 v[216:219], v163 offset:6144
	ds_read_b128 v[220:223], v163 offset:7168
	global_load_lds_dwordx4 v[224:225], off
	v_lshl_add_u64 v[224:225], s[28:29], 0, v[148:149]
	s_add_i32 m0, s58, 0xe000
	s_nop 0
	global_load_lds_dwordx4 v[224:225], off
	s_waitcnt vmcnt(8)
	s_waitcnt lgkmcnt(0)
	s_barrier
	v_mfma_f32_16x16x32_bf16 v[42:45], v[154:157], v[192:195], v[42:45]
	v_mfma_f32_16x16x32_bf16 v[26:29], v[168:171], v[192:195], v[26:29]
	v_mfma_f32_16x16x32_bf16 v[54:57], v[154:157], v[200:203], v[54:57]
	v_mfma_f32_16x16x32_bf16 v[38:41], v[168:171], v[200:203], v[38:41]
	v_mfma_f32_16x16x32_bf16 v[66:69], v[154:157], v[208:211], v[66:69]
	v_mfma_f32_16x16x32_bf16 v[50:53], v[168:171], v[208:211], v[50:53]
	v_mfma_f32_16x16x32_bf16 v[62:65], v[154:157], v[216:219], v[62:65]
	v_mfma_f32_16x16x32_bf16 v[46:49], v[168:171], v[216:219], v[46:49]
	v_mfma_f32_16x16x32_bf16 v[42:45], v[164:167], v[196:199], v[42:45]
	v_mfma_f32_16x16x32_bf16 v[26:29], v[172:175], v[196:199], v[26:29]
	v_mfma_f32_16x16x32_bf16 v[54:57], v[164:167], v[204:207], v[54:57]
	v_mfma_f32_16x16x32_bf16 v[38:41], v[172:175], v[204:207], v[38:41]
	v_mfma_f32_16x16x32_bf16 v[66:69], v[164:167], v[212:215], v[66:69]
	v_mfma_f32_16x16x32_bf16 v[50:53], v[172:175], v[212:215], v[50:53]
	v_mfma_f32_16x16x32_bf16 v[62:65], v[164:167], v[220:223], v[62:65]
	v_mfma_f32_16x16x32_bf16 v[46:49], v[172:175], v[220:223], v[46:49]
	v_mfma_f32_16x16x32_bf16 v[14:17], v[176:179], v[192:195], v[14:17]
	v_mfma_f32_16x16x32_bf16 v[2:5], v[184:187], v[192:195], v[2:5]
	v_mfma_f32_16x16x32_bf16 v[22:25], v[176:179], v[200:203], v[22:25]
	v_mfma_f32_16x16x32_bf16 v[6:9], v[184:187], v[200:203], v[6:9]
	v_mfma_f32_16x16x32_bf16 v[30:33], v[176:179], v[208:211], v[30:33]
	v_mfma_f32_16x16x32_bf16 v[10:13], v[184:187], v[208:211], v[10:13]
	v_mfma_f32_16x16x32_bf16 v[34:37], v[176:179], v[216:219], v[34:37]
	v_mfma_f32_16x16x32_bf16 v[18:21], v[184:187], v[216:219], v[18:21]
	v_mfma_f32_16x16x32_bf16 v[14:17], v[180:183], v[196:199], v[14:17]
	v_mfma_f32_16x16x32_bf16 v[2:5], v[188:191], v[196:199], v[2:5]
	v_mfma_f32_16x16x32_bf16 v[22:25], v[180:183], v[204:207], v[22:25]
	v_mfma_f32_16x16x32_bf16 v[6:9], v[188:191], v[204:207], v[6:9]
	v_mfma_f32_16x16x32_bf16 v[30:33], v[180:183], v[212:215], v[30:33]
	v_mfma_f32_16x16x32_bf16 v[10:13], v[188:191], v[212:215], v[10:13]
	v_mfma_f32_16x16x32_bf16 v[34:37], v[180:183], v[220:223], v[34:37]
	v_mfma_f32_16x16x32_bf16 v[18:21], v[188:191], v[220:223], v[18:21]
	s_barrier
	s_add_i32 s50, s70, s54
	v_lshl_add_u64 v[224:225], s[30:31], 0, v[134:135]
	s_mov_b32 m0, s50
	ds_read_b128 v[192:195], v163 offset:16384
	ds_read_b128 v[196:199], v163 offset:17408
	ds_read_b128 v[200:203], v163 offset:18432
	ds_read_b128 v[204:207], v163 offset:19456
	ds_read_b128 v[208:211], v163 offset:20480
	ds_read_b128 v[212:215], v163 offset:21504
	ds_read_b128 v[216:219], v163 offset:22528
	ds_read_b128 v[220:223], v163 offset:23552
	global_load_lds_dwordx4 v[224:225], off
	s_add_i32 m0, s50, 0x2000
	s_add_u32 s76, s30, 0x40000
	v_lshl_add_u64 v[226:227], s[30:31], 0, v[130:131]
	s_addc_u32 s77, s31, 0
	s_add_i32 s50, s71, s54
	global_load_lds_dwordx4 v[226:227], off
	v_lshl_add_u64 v[228:229], s[76:77], 0, v[134:135]
	s_mov_b32 m0, s50
	v_lshl_add_u64 v[230:231], s[34:35], 0, v[132:133]
	global_load_lds_dwordx4 v[228:229], off
	v_lshl_add_u64 v[228:229], s[76:77], 0, v[130:131]
	s_add_i32 m0, s50, 0x2000
	s_nop 0
	global_load_lds_dwordx4 v[228:229], off
	v_lshl_add_u64 v[228:229], s[34:35], 0, v[136:137]
	s_mov_b32 m0, s58
	s_nop 0
	global_load_lds_dwordx4 v[228:229], off
	s_mov_b32 m0, s59
	s_nop 0
	global_load_lds_dwordx4 v[230:231], off
	s_waitcnt vmcnt(8)
	s_waitcnt lgkmcnt(0)
	s_barrier
	v_mfma_f32_16x16x32_bf16 v[110:113], v[154:157], v[192:195], v[110:113]
	v_mfma_f32_16x16x32_bf16 v[86:89], v[168:171], v[192:195], v[86:89]
	v_mfma_f32_16x16x32_bf16 v[106:109], v[154:157], v[200:203], v[106:109]
	v_mfma_f32_16x16x32_bf16 v[82:85], v[168:171], v[200:203], v[82:85]
	v_mfma_f32_16x16x32_bf16 v[118:121], v[154:157], v[208:211], v[118:121]
	v_mfma_f32_16x16x32_bf16 v[94:97], v[168:171], v[208:211], v[94:97]
	v_mfma_f32_16x16x32_bf16 v[126:129], v[154:157], v[216:219], v[126:129]
	v_mfma_f32_16x16x32_bf16 v[102:105], v[168:171], v[216:219], v[102:105]
	v_mfma_f32_16x16x32_bf16 v[110:113], v[164:167], v[196:199], v[110:113]
	v_mfma_f32_16x16x32_bf16 v[86:89], v[172:175], v[196:199], v[86:89]
	v_mfma_f32_16x16x32_bf16 v[106:109], v[164:167], v[204:207], v[106:109]
	v_mfma_f32_16x16x32_bf16 v[82:85], v[172:175], v[204:207], v[82:85]
	v_mfma_f32_16x16x32_bf16 v[118:121], v[164:167], v[212:215], v[118:121]
	v_mfma_f32_16x16x32_bf16 v[94:97], v[172:175], v[212:215], v[94:97]
	v_mfma_f32_16x16x32_bf16 v[126:129], v[164:167], v[220:223], v[126:129]
	v_mfma_f32_16x16x32_bf16 v[102:105], v[172:175], v[220:223], v[102:105]
	v_mfma_f32_16x16x32_bf16 v[70:73], v[176:179], v[192:195], v[70:73]
	v_mfma_f32_16x16x32_bf16 v[58:61], v[184:187], v[192:195], v[58:61]
	v_mfma_f32_16x16x32_bf16 v[74:77], v[176:179], v[200:203], v[74:77]
	v_mfma_f32_16x16x32_bf16 v[78:81], v[184:187], v[200:203], v[78:81]
	v_mfma_f32_16x16x32_bf16 v[114:117], v[176:179], v[208:211], v[114:117]
	v_mfma_f32_16x16x32_bf16 v[90:93], v[184:187], v[208:211], v[90:93]
	v_mfma_f32_16x16x32_bf16 v[122:125], v[176:179], v[216:219], v[122:125]
	v_mfma_f32_16x16x32_bf16 v[98:101], v[184:187], v[216:219], v[98:101]
	v_mfma_f32_16x16x32_bf16 v[70:73], v[180:183], v[196:199], v[70:73]
	v_mfma_f32_16x16x32_bf16 v[58:61], v[188:191], v[196:199], v[58:61]
	v_mfma_f32_16x16x32_bf16 v[74:77], v[180:183], v[204:207], v[74:77]
	v_mfma_f32_16x16x32_bf16 v[78:81], v[188:191], v[204:207], v[78:81]
	v_mfma_f32_16x16x32_bf16 v[114:117], v[180:183], v[212:215], v[114:117]
	v_mfma_f32_16x16x32_bf16 v[90:93], v[188:191], v[212:215], v[90:93]
	v_mfma_f32_16x16x32_bf16 v[122:125], v[180:183], v[220:223], v[122:125]
	v_mfma_f32_16x16x32_bf16 v[98:101], v[188:191], v[220:223], v[98:101]
	s_barrier
	s_add_i32 s50, 0, 0x18000
	s_add_i32 s51, 0, 0x1c000
	v_add_u32_e32 v172, s50, v160
	v_add_u32_e32 v188, s51, v160
	ds_read_b128 v[154:157], v172
	ds_read_b128 v[164:167], v172 offset:1024
	ds_read_b128 v[168:171], v172 offset:2048
	ds_read_b128 v[172:175], v172 offset:3072
	ds_read_b128 v[176:179], v188
	ds_read_b128 v[180:183], v188 offset:1024
	ds_read_b128 v[184:187], v188 offset:2048
	ds_read_b128 v[188:191], v188 offset:3072
	s_add_u32 s34, s34, 0x40000
	s_addc_u32 s35, s35, 0
	s_mov_b32 m0, s60
	v_lshl_add_u64 v[232:233], s[34:35], 0, v[136:137]
	ds_read_b128 v[192:195], v163 offset:32768
	ds_read_b128 v[196:199], v163 offset:33792
	ds_read_b128 v[200:203], v163 offset:34816
	ds_read_b128 v[204:207], v163 offset:35840
	ds_read_b128 v[208:211], v163 offset:36864
	ds_read_b128 v[212:215], v163 offset:37888
	ds_read_b128 v[216:219], v163 offset:38912
	ds_read_b128 v[220:223], v163 offset:39936
	global_load_lds_dwordx4 v[232:233], off
	v_lshl_add_u64 v[232:233], s[34:35], 0, v[132:133]
	s_mov_b32 m0, s61
	s_nop 0
	global_load_lds_dwordx4 v[232:233], off
	s_waitcnt vmcnt(8)
	s_waitcnt lgkmcnt(0)
	s_barrier
	v_mfma_f32_16x16x32_bf16 v[42:45], v[154:157], v[192:195], v[42:45]
	v_mfma_f32_16x16x32_bf16 v[26:29], v[168:171], v[192:195], v[26:29]
	v_mfma_f32_16x16x32_bf16 v[54:57], v[154:157], v[200:203], v[54:57]
	v_mfma_f32_16x16x32_bf16 v[38:41], v[168:171], v[200:203], v[38:41]
	v_mfma_f32_16x16x32_bf16 v[66:69], v[154:157], v[208:211], v[66:69]
	v_mfma_f32_16x16x32_bf16 v[50:53], v[168:171], v[208:211], v[50:53]
	v_mfma_f32_16x16x32_bf16 v[62:65], v[154:157], v[216:219], v[62:65]
	v_mfma_f32_16x16x32_bf16 v[46:49], v[168:171], v[216:219], v[46:49]
	v_mfma_f32_16x16x32_bf16 v[42:45], v[164:167], v[196:199], v[42:45]
	v_mfma_f32_16x16x32_bf16 v[26:29], v[172:175], v[196:199], v[26:29]
	v_mfma_f32_16x16x32_bf16 v[54:57], v[164:167], v[204:207], v[54:57]
	v_mfma_f32_16x16x32_bf16 v[38:41], v[172:175], v[204:207], v[38:41]
	v_mfma_f32_16x16x32_bf16 v[66:69], v[164:167], v[212:215], v[66:69]
	v_mfma_f32_16x16x32_bf16 v[50:53], v[172:175], v[212:215], v[50:53]
	v_mfma_f32_16x16x32_bf16 v[62:65], v[164:167], v[220:223], v[62:65]
	v_mfma_f32_16x16x32_bf16 v[46:49], v[172:175], v[220:223], v[46:49]
	v_mfma_f32_16x16x32_bf16 v[14:17], v[176:179], v[192:195], v[14:17]
	v_mfma_f32_16x16x32_bf16 v[2:5], v[184:187], v[192:195], v[2:5]
	v_mfma_f32_16x16x32_bf16 v[22:25], v[176:179], v[200:203], v[22:25]
	v_mfma_f32_16x16x32_bf16 v[6:9], v[184:187], v[200:203], v[6:9]
	v_mfma_f32_16x16x32_bf16 v[30:33], v[176:179], v[208:211], v[30:33]
	v_mfma_f32_16x16x32_bf16 v[10:13], v[184:187], v[208:211], v[10:13]
	v_mfma_f32_16x16x32_bf16 v[34:37], v[176:179], v[216:219], v[34:37]
	v_mfma_f32_16x16x32_bf16 v[18:21], v[184:187], v[216:219], v[18:21]
	v_mfma_f32_16x16x32_bf16 v[14:17], v[180:183], v[196:199], v[14:17]
	v_mfma_f32_16x16x32_bf16 v[2:5], v[188:191], v[196:199], v[2:5]
	v_mfma_f32_16x16x32_bf16 v[22:25], v[180:183], v[204:207], v[22:25]
	v_mfma_f32_16x16x32_bf16 v[6:9], v[188:191], v[204:207], v[6:9]
	v_mfma_f32_16x16x32_bf16 v[30:33], v[180:183], v[212:215], v[30:33]
	v_mfma_f32_16x16x32_bf16 v[10:13], v[188:191], v[212:215], v[10:13]
	v_mfma_f32_16x16x32_bf16 v[34:37], v[180:183], v[220:223], v[34:37]
	v_mfma_f32_16x16x32_bf16 v[18:21], v[188:191], v[220:223], v[18:21]
	s_barrier
	s_add_i32 s34, s50, s54
	v_lshl_add_u64 v[224:225], v[224:225], 0, s[10:11]
	s_mov_b32 m0, s34
	ds_read_b128 v[192:195], v163 offset:49152
	ds_read_b128 v[196:199], v163 offset:50176
	ds_read_b128 v[200:203], v163 offset:51200
	ds_read_b128 v[204:207], v163 offset:52224
	ds_read_b128 v[208:211], v163 offset:53248
	ds_read_b128 v[212:215], v163 offset:54272
	ds_read_b128 v[216:219], v163 offset:55296
	ds_read_b128 v[220:223], v163 offset:56320
	global_load_lds_dwordx4 v[224:225], off
	s_add_i32 m0, s34, 0x2000
	s_add_u32 s30, s30, 0x40080
	v_lshl_add_u64 v[224:225], v[226:227], 0, s[10:11]
	s_addc_u32 s31, s31, 0
	s_add_i32 s34, s51, s54
	global_load_lds_dwordx4 v[224:225], off
	v_lshl_add_u64 v[224:225], s[30:31], 0, v[134:135]
	s_mov_b32 m0, s34
	s_nop 0
	global_load_lds_dwordx4 v[224:225], off
	v_lshl_add_u64 v[224:225], s[30:31], 0, v[130:131]
	s_add_i32 m0, s34, 0x2000
	s_nop 0
	global_load_lds_dwordx4 v[224:225], off
	v_lshl_add_u64 v[224:225], v[228:229], 0, s[10:11]
	s_mov_b32 m0, s65
	s_nop 0
	global_load_lds_dwordx4 v[224:225], off
	v_lshl_add_u64 v[224:225], v[230:231], 0, s[10:11]
	s_mov_b32 m0, s66
	s_nop 0
	global_load_lds_dwordx4 v[224:225], off
	s_waitcnt vmcnt(8)
	s_waitcnt lgkmcnt(0)
	s_barrier
	v_mfma_f32_16x16x32_bf16 v[110:113], v[154:157], v[192:195], v[110:113]
	v_mfma_f32_16x16x32_bf16 v[86:89], v[168:171], v[192:195], v[86:89]
	v_mfma_f32_16x16x32_bf16 v[106:109], v[154:157], v[200:203], v[106:109]
	v_mfma_f32_16x16x32_bf16 v[82:85], v[168:171], v[200:203], v[82:85]
	v_mfma_f32_16x16x32_bf16 v[118:121], v[154:157], v[208:211], v[118:121]
	v_mfma_f32_16x16x32_bf16 v[94:97], v[168:171], v[208:211], v[94:97]
	v_mfma_f32_16x16x32_bf16 v[126:129], v[154:157], v[216:219], v[126:129]
	v_mfma_f32_16x16x32_bf16 v[102:105], v[168:171], v[216:219], v[102:105]
	v_mfma_f32_16x16x32_bf16 v[110:113], v[164:167], v[196:199], v[110:113]
	v_mfma_f32_16x16x32_bf16 v[86:89], v[172:175], v[196:199], v[86:89]
	v_mfma_f32_16x16x32_bf16 v[106:109], v[164:167], v[204:207], v[106:109]
	v_mfma_f32_16x16x32_bf16 v[82:85], v[172:175], v[204:207], v[82:85]
	v_mfma_f32_16x16x32_bf16 v[118:121], v[164:167], v[212:215], v[118:121]
	v_mfma_f32_16x16x32_bf16 v[94:97], v[172:175], v[212:215], v[94:97]
	v_mfma_f32_16x16x32_bf16 v[126:129], v[164:167], v[220:223], v[126:129]
	v_mfma_f32_16x16x32_bf16 v[102:105], v[172:175], v[220:223], v[102:105]
	v_mfma_f32_16x16x32_bf16 v[70:73], v[176:179], v[192:195], v[70:73]
	v_mfma_f32_16x16x32_bf16 v[58:61], v[184:187], v[192:195], v[58:61]
	v_mfma_f32_16x16x32_bf16 v[74:77], v[176:179], v[200:203], v[74:77]
	v_mfma_f32_16x16x32_bf16 v[78:81], v[184:187], v[200:203], v[78:81]
	v_mfma_f32_16x16x32_bf16 v[114:117], v[176:179], v[208:211], v[114:117]
	v_mfma_f32_16x16x32_bf16 v[90:93], v[184:187], v[208:211], v[90:93]
	v_mfma_f32_16x16x32_bf16 v[122:125], v[176:179], v[216:219], v[122:125]
	v_mfma_f32_16x16x32_bf16 v[98:101], v[184:187], v[216:219], v[98:101]
	v_mfma_f32_16x16x32_bf16 v[70:73], v[180:183], v[196:199], v[70:73]
	v_mfma_f32_16x16x32_bf16 v[58:61], v[188:191], v[196:199], v[58:61]
	v_mfma_f32_16x16x32_bf16 v[74:77], v[180:183], v[204:207], v[74:77]
	v_mfma_f32_16x16x32_bf16 v[78:81], v[188:191], v[204:207], v[78:81]
	v_mfma_f32_16x16x32_bf16 v[114:117], v[180:183], v[212:215], v[114:117]
	v_mfma_f32_16x16x32_bf16 v[90:93], v[188:191], v[212:215], v[90:93]
	v_mfma_f32_16x16x32_bf16 v[122:125], v[180:183], v[220:223], v[122:125]
	v_mfma_f32_16x16x32_bf16 v[98:101], v[188:191], v[220:223], v[98:101]
	s_barrier
	s_add_u32 s28, s28, 0x100
	s_addc_u32 s29, s29, 0
	s_add_u32 s17, s17, 0x100
	s_addc_u32 s19, s19, 0
	s_cmp_ge_i32 s75, s62
	s_mov_b32 s30, s75
	s_cbranch_scc0 .LBB0_256

.LBB0_351:
	v_add_u32_e32 v81, s62, v78
	s_waitcnt lgkmcnt(0)
	ds_read_b128 v[82:85], v81
	ds_read_b128 v[86:89], v81 offset:1024
	ds_read_b128 v[90:93], v81 offset:2048
	ds_read_b128 v[94:97], v81 offset:3072
	s_add_i32 s72, s24, 2
	s_add_u32 s22, s20, 0x100
	s_addc_u32 s23, s21, 0
	s_cmp_eq_u32 s61, s24
	s_cselect_b32 s24, s16, s70
	s_cselect_b32 s27, s15, s23
	s_cselect_b32 s26, s14, s22
	s_cselect_b32 s25, s17, s71
	s_mov_b32 m0, s63
	v_lshl_add_u64 v[130:131], s[20:21], 0, v[74:75]
	ds_read_b128 v[98:101], v79
	ds_read_b128 v[102:105], v79 offset:1024
	ds_read_b128 v[106:109], v79 offset:2048
	ds_read_b128 v[110:113], v79 offset:3072
	ds_read_b128 v[114:117], v79 offset:4096
	ds_read_b128 v[118:121], v79 offset:5120
	ds_read_b128 v[122:125], v79 offset:6144
	ds_read_b128 v[126:129], v79 offset:7168
	global_load_lds_dwordx4 v[130:131], off
	v_lshl_add_u64 v[130:131], s[20:21], 0, v[76:77]
	s_mov_b32 m0, s64
	s_nop 0
	global_load_lds_dwordx4 v[130:131], off
	s_waitcnt vmcnt(8)
	s_waitcnt lgkmcnt(0)
	s_barrier
	v_mfma_f32_16x16x32_bf16 v[62:65], v[82:85], v[98:101], v[62:65]
	v_mfma_f32_16x16x32_bf16 v[58:61], v[90:93], v[98:101], v[58:61]
	v_mfma_f32_16x16x32_bf16 v[54:57], v[82:85], v[106:109], v[54:57]
	v_mfma_f32_16x16x32_bf16 v[50:53], v[90:93], v[106:109], v[50:53]
	v_mfma_f32_16x16x32_bf16 v[46:49], v[82:85], v[114:117], v[46:49]
	v_mfma_f32_16x16x32_bf16 v[42:45], v[90:93], v[114:117], v[42:45]
	v_mfma_f32_16x16x32_bf16 v[34:37], v[82:85], v[122:125], v[34:37]
	v_mfma_f32_16x16x32_bf16 v[26:29], v[90:93], v[122:125], v[26:29]
	v_mfma_f32_16x16x32_bf16 v[62:65], v[86:89], v[102:105], v[62:65]
	v_mfma_f32_16x16x32_bf16 v[58:61], v[94:97], v[102:105], v[58:61]
	v_mfma_f32_16x16x32_bf16 v[54:57], v[86:89], v[110:113], v[54:57]
	v_mfma_f32_16x16x32_bf16 v[50:53], v[94:97], v[110:113], v[50:53]
	v_mfma_f32_16x16x32_bf16 v[46:49], v[86:89], v[118:121], v[46:49]
	v_mfma_f32_16x16x32_bf16 v[42:45], v[94:97], v[118:121], v[42:45]
	v_mfma_f32_16x16x32_bf16 v[34:37], v[86:89], v[126:129], v[34:37]
	v_mfma_f32_16x16x32_bf16 v[26:29], v[94:97], v[126:129], v[26:29]
	s_barrier
	s_mov_b32 m0, s65
	v_lshl_add_u64 v[130:131], s[24:25], 0, v[70:71]
	s_add_u32 s20, s24, 0x10000
	ds_read_b128 v[98:101], v79 offset:16384
	ds_read_b128 v[102:105], v79 offset:17408
	ds_read_b128 v[106:109], v79 offset:18432
	ds_read_b128 v[110:113], v79 offset:19456
	ds_read_b128 v[114:117], v79 offset:20480
	ds_read_b128 v[118:121], v79 offset:21504
	ds_read_b128 v[122:125], v79 offset:22528
	ds_read_b128 v[126:129], v79 offset:23552
	global_load_lds_dwordx4 v[130:131], off
	v_lshl_add_u64 v[132:133], s[24:25], 0, v[66:67]
	s_mov_b32 m0, s66
	s_addc_u32 s21, s25, 0
	global_load_lds_dwordx4 v[132:133], off
	v_lshl_add_u64 v[134:135], s[20:21], 0, v[70:71]
	s_mov_b32 m0, s34
	v_lshl_add_u64 v[136:137], s[26:27], 0, v[68:69]
	global_load_lds_dwordx4 v[134:135], off
	v_lshl_add_u64 v[134:135], s[20:21], 0, v[66:67]
	s_mov_b32 m0, s35
	s_nop 0
	global_load_lds_dwordx4 v[134:135], off
	v_lshl_add_u64 v[134:135], s[26:27], 0, v[72:73]
	s_mov_b32 m0, s31
	s_nop 0
	global_load_lds_dwordx4 v[134:135], off
	s_mov_b32 m0, s52
	s_nop 0
	global_load_lds_dwordx4 v[136:137], off
	s_waitcnt vmcnt(8)
	s_waitcnt lgkmcnt(0)
	s_barrier
	v_mfma_f32_16x16x32_bf16 v[38:41], v[82:85], v[98:101], v[38:41]
	v_mfma_f32_16x16x32_bf16 v[30:33], v[90:93], v[98:101], v[30:33]
	v_mfma_f32_16x16x32_bf16 v[22:25], v[82:85], v[106:109], v[22:25]
	v_mfma_f32_16x16x32_bf16 v[18:21], v[90:93], v[106:109], v[18:21]
	v_mfma_f32_16x16x32_bf16 v[14:17], v[82:85], v[114:117], v[14:17]
	v_mfma_f32_16x16x32_bf16 v[10:13], v[90:93], v[114:117], v[10:13]
	v_mfma_f32_16x16x32_bf16 v[6:9], v[82:85], v[122:125], v[6:9]
	v_mfma_f32_16x16x32_bf16 v[2:5], v[90:93], v[122:125], v[2:5]
	v_mfma_f32_16x16x32_bf16 v[38:41], v[86:89], v[102:105], v[38:41]
	v_mfma_f32_16x16x32_bf16 v[30:33], v[94:97], v[102:105], v[30:33]
	v_mfma_f32_16x16x32_bf16 v[22:25], v[86:89], v[110:113], v[22:25]
	v_mfma_f32_16x16x32_bf16 v[18:21], v[94:97], v[110:113], v[18:21]
	v_mfma_f32_16x16x32_bf16 v[14:17], v[86:89], v[118:121], v[14:17]
	v_mfma_f32_16x16x32_bf16 v[10:13], v[94:97], v[118:121], v[10:13]
	v_mfma_f32_16x16x32_bf16 v[6:9], v[86:89], v[126:129], v[6:9]
	v_mfma_f32_16x16x32_bf16 v[2:5], v[94:97], v[126:129], v[2:5]
	s_barrier
	v_add_u32_e32 v81, s67, v78
	ds_read_b128 v[82:85], v81
	ds_read_b128 v[86:89], v81 offset:1024
	ds_read_b128 v[90:93], v81 offset:2048
	ds_read_b128 v[94:97], v81 offset:3072
	s_add_u32 s20, s26, 0x18000
	s_addc_u32 s21, s27, 0
	s_mov_b32 m0, s53
	v_lshl_add_u64 v[138:139], s[20:21], 0, v[72:73]
	ds_read_b128 v[98:101], v79 offset:32768
	ds_read_b128 v[102:105], v79 offset:33792
	ds_read_b128 v[106:109], v79 offset:34816
	ds_read_b128 v[110:113], v79 offset:35840
	ds_read_b128 v[114:117], v79 offset:36864
	ds_read_b128 v[118:121], v79 offset:37888
	ds_read_b128 v[122:125], v79 offset:38912
	ds_read_b128 v[126:129], v79 offset:39936
	global_load_lds_dwordx4 v[138:139], off
	v_lshl_add_u64 v[138:139], s[20:21], 0, v[68:69]
	s_mov_b32 m0, s54
	s_nop 0
	global_load_lds_dwordx4 v[138:139], off
	s_waitcnt vmcnt(8)
	s_waitcnt lgkmcnt(0)
	s_barrier
	v_mfma_f32_16x16x32_bf16 v[62:65], v[82:85], v[98:101], v[62:65]
	v_mfma_f32_16x16x32_bf16 v[58:61], v[90:93], v[98:101], v[58:61]
	v_mfma_f32_16x16x32_bf16 v[54:57], v[82:85], v[106:109], v[54:57]
	v_mfma_f32_16x16x32_bf16 v[50:53], v[90:93], v[106:109], v[50:53]
	v_mfma_f32_16x16x32_bf16 v[46:49], v[82:85], v[114:117], v[46:49]
	v_mfma_f32_16x16x32_bf16 v[42:45], v[90:93], v[114:117], v[42:45]
	v_mfma_f32_16x16x32_bf16 v[34:37], v[82:85], v[122:125], v[34:37]
	v_mfma_f32_16x16x32_bf16 v[26:29], v[90:93], v[122:125], v[26:29]
	v_mfma_f32_16x16x32_bf16 v[62:65], v[86:89], v[102:105], v[62:65]
	v_mfma_f32_16x16x32_bf16 v[58:61], v[94:97], v[102:105], v[58:61]
	v_mfma_f32_16x16x32_bf16 v[54:57], v[86:89], v[110:113], v[54:57]
	v_mfma_f32_16x16x32_bf16 v[50:53], v[94:97], v[110:113], v[50:53]
	v_mfma_f32_16x16x32_bf16 v[46:49], v[86:89], v[118:121], v[46:49]
	v_mfma_f32_16x16x32_bf16 v[42:45], v[94:97], v[118:121], v[42:45]
	v_mfma_f32_16x16x32_bf16 v[34:37], v[86:89], v[126:129], v[34:37]
	v_mfma_f32_16x16x32_bf16 v[26:29], v[94:97], v[126:129], v[26:29]
	s_barrier
	s_mov_b32 m0, s68
	v_lshl_add_u64 v[130:131], v[130:131], 0, s[6:7]
	s_add_u32 s20, s24, 0x10080
	ds_read_b128 v[98:101], v79 offset:49152
	ds_read_b128 v[102:105], v79 offset:50176
	ds_read_b128 v[106:109], v79 offset:51200
	ds_read_b128 v[110:113], v79 offset:52224
	ds_read_b128 v[114:117], v79 offset:53248
	ds_read_b128 v[118:121], v79 offset:54272
	ds_read_b128 v[122:125], v79 offset:55296
	ds_read_b128 v[126:129], v79 offset:56320
	global_load_lds_dwordx4 v[130:131], off
	v_lshl_add_u64 v[130:131], v[132:133], 0, s[6:7]
	s_mov_b32 m0, s69
	s_addc_u32 s21, s25, 0
	global_load_lds_dwordx4 v[130:131], off
	v_lshl_add_u64 v[130:131], s[20:21], 0, v[70:71]
	s_mov_b32 m0, s59
	s_nop 0
	global_load_lds_dwordx4 v[130:131], off
	v_lshl_add_u64 v[130:131], s[20:21], 0, v[66:67]
	s_mov_b32 m0, s60
	s_nop 0
	global_load_lds_dwordx4 v[130:131], off
	v_lshl_add_u64 v[130:131], v[134:135], 0, s[6:7]
	s_mov_b32 m0, s57
	s_nop 0
	global_load_lds_dwordx4 v[130:131], off
	v_lshl_add_u64 v[130:131], v[136:137], 0, s[6:7]
	s_mov_b32 m0, s58
	s_nop 0
	global_load_lds_dwordx4 v[130:131], off
	s_waitcnt vmcnt(8)
	s_waitcnt lgkmcnt(0)
	s_barrier
	v_mfma_f32_16x16x32_bf16 v[38:41], v[82:85], v[98:101], v[38:41]
	v_mfma_f32_16x16x32_bf16 v[30:33], v[90:93], v[98:101], v[30:33]
	v_mfma_f32_16x16x32_bf16 v[22:25], v[82:85], v[106:109], v[22:25]
	v_mfma_f32_16x16x32_bf16 v[18:21], v[90:93], v[106:109], v[18:21]
	v_mfma_f32_16x16x32_bf16 v[14:17], v[82:85], v[114:117], v[14:17]
	v_mfma_f32_16x16x32_bf16 v[10:13], v[90:93], v[114:117], v[10:13]
	v_mfma_f32_16x16x32_bf16 v[6:9], v[82:85], v[122:125], v[6:9]
	v_mfma_f32_16x16x32_bf16 v[2:5], v[90:93], v[122:125], v[2:5]
	v_mfma_f32_16x16x32_bf16 v[38:41], v[86:89], v[102:105], v[38:41]
	v_mfma_f32_16x16x32_bf16 v[30:33], v[94:97], v[102:105], v[30:33]
	v_mfma_f32_16x16x32_bf16 v[22:25], v[86:89], v[110:113], v[22:25]
	v_mfma_f32_16x16x32_bf16 v[18:21], v[94:97], v[110:113], v[18:21]
	v_mfma_f32_16x16x32_bf16 v[14:17], v[86:89], v[118:121], v[14:17]
	v_mfma_f32_16x16x32_bf16 v[10:13], v[94:97], v[118:121], v[10:13]
	v_mfma_f32_16x16x32_bf16 v[6:9], v[86:89], v[126:129], v[6:9]
	v_mfma_f32_16x16x32_bf16 v[2:5], v[94:97], v[126:129], v[2:5]
	s_barrier
	s_add_u32 s70, s70, 0x100
	s_addc_u32 s71, s71, 0
	s_cmp_ge_i32 s72, s56
	s_mov_b64 s[20:21], s[22:23]
	s_mov_b32 s24, s72
	s_cbranch_scc0 .LBB0_351

.LBB0_468:
	v_add_u32_e32 v144, s62, v1
	ds_read_b128 v[150:153], v144
	ds_read_b128 v[154:157], v144 offset:1024
	ds_read_b128 v[158:161], v144 offset:2048
	ds_read_b128 v[162:165], v144 offset:3072
	v_add_u32_e32 v144, s63, v1
	ds_read_b128 v[166:169], v144
	ds_read_b128 v[170:173], v144 offset:1024
	ds_read_b128 v[174:177], v144 offset:2048
	ds_read_b128 v[178:181], v144 offset:3072
	s_add_i32 s77, s26, 2
	s_add_u32 s24, s22, 0x100
	s_addc_u32 s25, s23, 0
	s_cmp_eq_u32 s61, s26
	s_cselect_b32 s26, s16, s75
	s_cselect_b32 s29, s15, s25
	s_cselect_b32 s28, s14, s24
	s_cselect_b32 s27, s17, s76
	s_mov_b32 m0, s64
	v_lshl_add_u64 v[144:145], s[22:23], 0, v[140:141]
	ds_read_b128 v[182:185], v149
	ds_read_b128 v[186:189], v149 offset:1024
	ds_read_b128 v[190:193], v149 offset:2048
	ds_read_b128 v[194:197], v149 offset:3072
	ds_read_b128 v[198:201], v149 offset:4096
	ds_read_b128 v[202:205], v149 offset:5120
	ds_read_b128 v[206:209], v149 offset:6144
	ds_read_b128 v[210:213], v149 offset:7168
	global_load_lds_dwordx4 v[144:145], off
	v_lshl_add_u64 v[144:145], s[22:23], 0, v[142:143]
	s_mov_b32 m0, s65
	s_nop 0
	global_load_lds_dwordx4 v[144:145], off
	s_waitcnt vmcnt(8)
	s_waitcnt lgkmcnt(0)
	s_barrier
	v_mfma_f32_16x16x32_bf16 v[126:129], v[150:153], v[182:185], v[126:129]
	v_mfma_f32_16x16x32_bf16 v[122:125], v[158:161], v[182:185], v[122:125]
	v_mfma_f32_16x16x32_bf16 v[110:113], v[150:153], v[190:193], v[110:113]
	v_mfma_f32_16x16x32_bf16 v[106:109], v[158:161], v[190:193], v[106:109]
	v_mfma_f32_16x16x32_bf16 v[94:97], v[150:153], v[198:201], v[94:97]
	v_mfma_f32_16x16x32_bf16 v[90:93], v[158:161], v[198:201], v[90:93]
	v_mfma_f32_16x16x32_bf16 v[78:81], v[150:153], v[206:209], v[78:81]
	v_mfma_f32_16x16x32_bf16 v[74:77], v[158:161], v[206:209], v[74:77]
	v_mfma_f32_16x16x32_bf16 v[126:129], v[154:157], v[186:189], v[126:129]
	v_mfma_f32_16x16x32_bf16 v[122:125], v[162:165], v[186:189], v[122:125]
	v_mfma_f32_16x16x32_bf16 v[110:113], v[154:157], v[194:197], v[110:113]
	v_mfma_f32_16x16x32_bf16 v[106:109], v[162:165], v[194:197], v[106:109]
	v_mfma_f32_16x16x32_bf16 v[94:97], v[154:157], v[202:205], v[94:97]
	v_mfma_f32_16x16x32_bf16 v[90:93], v[162:165], v[202:205], v[90:93]
	v_mfma_f32_16x16x32_bf16 v[78:81], v[154:157], v[210:213], v[78:81]
	v_mfma_f32_16x16x32_bf16 v[74:77], v[162:165], v[210:213], v[74:77]
	v_mfma_f32_16x16x32_bf16 v[118:121], v[166:169], v[182:185], v[118:121]
	v_mfma_f32_16x16x32_bf16 v[114:117], v[174:177], v[182:185], v[114:117]
	v_mfma_f32_16x16x32_bf16 v[102:105], v[166:169], v[190:193], v[102:105]
	v_mfma_f32_16x16x32_bf16 v[98:101], v[174:177], v[190:193], v[98:101]
	v_mfma_f32_16x16x32_bf16 v[86:89], v[166:169], v[198:201], v[86:89]
	v_mfma_f32_16x16x32_bf16 v[82:85], v[174:177], v[198:201], v[82:85]
	v_mfma_f32_16x16x32_bf16 v[70:73], v[166:169], v[206:209], v[70:73]
	v_mfma_f32_16x16x32_bf16 v[66:69], v[174:177], v[206:209], v[66:69]
	v_mfma_f32_16x16x32_bf16 v[118:121], v[170:173], v[186:189], v[118:121]
	v_mfma_f32_16x16x32_bf16 v[114:117], v[178:181], v[186:189], v[114:117]
	v_mfma_f32_16x16x32_bf16 v[102:105], v[170:173], v[194:197], v[102:105]
	v_mfma_f32_16x16x32_bf16 v[98:101], v[178:181], v[194:197], v[98:101]
	v_mfma_f32_16x16x32_bf16 v[86:89], v[170:173], v[202:205], v[86:89]
	v_mfma_f32_16x16x32_bf16 v[82:85], v[178:181], v[202:205], v[82:85]
	v_mfma_f32_16x16x32_bf16 v[70:73], v[170:173], v[210:213], v[70:73]
	v_mfma_f32_16x16x32_bf16 v[66:69], v[178:181], v[210:213], v[66:69]
	s_barrier
	s_mov_b32 m0, s66
	v_lshl_add_u64 v[144:145], s[26:27], 0, v[134:135]
	s_add_u32 s22, s26, 0x18000
	ds_read_b128 v[182:185], v149 offset:16384
	ds_read_b128 v[186:189], v149 offset:17408
	ds_read_b128 v[190:193], v149 offset:18432
	ds_read_b128 v[194:197], v149 offset:19456
	ds_read_b128 v[198:201], v149 offset:20480
	ds_read_b128 v[202:205], v149 offset:21504
	ds_read_b128 v[206:209], v149 offset:22528
	ds_read_b128 v[210:213], v149 offset:23552
	global_load_lds_dwordx4 v[144:145], off
	v_lshl_add_u64 v[214:215], s[26:27], 0, v[130:131]
	s_mov_b32 m0, s67
	s_addc_u32 s23, s27, 0
	global_load_lds_dwordx4 v[214:215], off
	v_lshl_add_u64 v[216:217], s[22:23], 0, v[134:135]
	s_mov_b32 m0, s68
	v_lshl_add_u64 v[218:219], s[28:29], 0, v[132:133]
	global_load_lds_dwordx4 v[216:217], off
	v_lshl_add_u64 v[216:217], s[22:23], 0, v[130:131]
	s_mov_b32 m0, s69
	s_nop 0
	global_load_lds_dwordx4 v[216:217], off
	v_lshl_add_u64 v[216:217], s[28:29], 0, v[136:137]
	s_mov_b32 m0, s34
	s_nop 0
	global_load_lds_dwordx4 v[216:217], off
	s_mov_b32 m0, s35
	s_nop 0
	global_load_lds_dwordx4 v[218:219], off
	s_waitcnt vmcnt(8)
	s_waitcnt lgkmcnt(0)
	s_barrier
	v_mfma_f32_16x16x32_bf16 v[62:65], v[150:153], v[182:185], v[62:65]
	v_mfma_f32_16x16x32_bf16 v[58:61], v[158:161], v[182:185], v[58:61]
	v_mfma_f32_16x16x32_bf16 v[46:49], v[150:153], v[190:193], v[46:49]
	v_mfma_f32_16x16x32_bf16 v[42:45], v[158:161], v[190:193], v[42:45]
	v_mfma_f32_16x16x32_bf16 v[30:33], v[150:153], v[198:201], v[30:33]
	v_mfma_f32_16x16x32_bf16 v[26:29], v[158:161], v[198:201], v[26:29]
	v_mfma_f32_16x16x32_bf16 v[14:17], v[150:153], v[206:209], v[14:17]
	v_mfma_f32_16x16x32_bf16 v[10:13], v[158:161], v[206:209], v[10:13]
	v_mfma_f32_16x16x32_bf16 v[62:65], v[154:157], v[186:189], v[62:65]
	v_mfma_f32_16x16x32_bf16 v[58:61], v[162:165], v[186:189], v[58:61]
	v_mfma_f32_16x16x32_bf16 v[46:49], v[154:157], v[194:197], v[46:49]
	v_mfma_f32_16x16x32_bf16 v[42:45], v[162:165], v[194:197], v[42:45]
	v_mfma_f32_16x16x32_bf16 v[30:33], v[154:157], v[202:205], v[30:33]
	v_mfma_f32_16x16x32_bf16 v[26:29], v[162:165], v[202:205], v[26:29]
	v_mfma_f32_16x16x32_bf16 v[14:17], v[154:157], v[210:213], v[14:17]
	v_mfma_f32_16x16x32_bf16 v[10:13], v[162:165], v[210:213], v[10:13]
	v_mfma_f32_16x16x32_bf16 v[54:57], v[166:169], v[182:185], v[54:57]
	v_mfma_f32_16x16x32_bf16 v[50:53], v[174:177], v[182:185], v[50:53]
	v_mfma_f32_16x16x32_bf16 v[38:41], v[166:169], v[190:193], v[38:41]
	v_mfma_f32_16x16x32_bf16 v[34:37], v[174:177], v[190:193], v[34:37]
	v_mfma_f32_16x16x32_bf16 v[22:25], v[166:169], v[198:201], v[22:25]
	v_mfma_f32_16x16x32_bf16 v[18:21], v[174:177], v[198:201], v[18:21]
	v_mfma_f32_16x16x32_bf16 v[6:9], v[166:169], v[206:209], v[6:9]
	v_mfma_f32_16x16x32_bf16 v[2:5], v[174:177], v[206:209], v[2:5]
	v_mfma_f32_16x16x32_bf16 v[54:57], v[170:173], v[186:189], v[54:57]
	v_mfma_f32_16x16x32_bf16 v[50:53], v[178:181], v[186:189], v[50:53]
	v_mfma_f32_16x16x32_bf16 v[38:41], v[170:173], v[194:197], v[38:41]
	v_mfma_f32_16x16x32_bf16 v[34:37], v[178:181], v[194:197], v[34:37]
	v_mfma_f32_16x16x32_bf16 v[22:25], v[170:173], v[202:205], v[22:25]
	v_mfma_f32_16x16x32_bf16 v[18:21], v[178:181], v[202:205], v[18:21]
	v_mfma_f32_16x16x32_bf16 v[6:9], v[170:173], v[210:213], v[6:9]
	v_mfma_f32_16x16x32_bf16 v[2:5], v[178:181], v[210:213], v[2:5]
	s_barrier
	v_add_u32_e32 v162, s70, v1
	v_add_u32_e32 v178, s71, v1
	ds_read_b128 v[150:153], v162
	ds_read_b128 v[154:157], v162 offset:1024
	ds_read_b128 v[158:161], v162 offset:2048
	ds_read_b128 v[162:165], v162 offset:3072
	ds_read_b128 v[166:169], v178
	ds_read_b128 v[170:173], v178 offset:1024
	ds_read_b128 v[174:177], v178 offset:2048
	ds_read_b128 v[178:181], v178 offset:3072
	s_add_u32 s22, s28, 0x18000
	s_addc_u32 s23, s29, 0
	s_mov_b32 m0, s52
	v_lshl_add_u64 v[220:221], s[22:23], 0, v[136:137]
	ds_read_b128 v[182:185], v149 offset:32768
	ds_read_b128 v[186:189], v149 offset:33792
	ds_read_b128 v[190:193], v149 offset:34816
	ds_read_b128 v[194:197], v149 offset:35840
	ds_read_b128 v[198:201], v149 offset:36864
	ds_read_b128 v[202:205], v149 offset:37888
	ds_read_b128 v[206:209], v149 offset:38912
	ds_read_b128 v[210:213], v149 offset:39936
	global_load_lds_dwordx4 v[220:221], off
	v_lshl_add_u64 v[220:221], s[22:23], 0, v[132:133]
	s_mov_b32 m0, s53
	s_nop 0
	global_load_lds_dwordx4 v[220:221], off
	s_waitcnt vmcnt(8)
	s_waitcnt lgkmcnt(0)
	s_barrier
	v_mfma_f32_16x16x32_bf16 v[126:129], v[150:153], v[182:185], v[126:129]
	v_mfma_f32_16x16x32_bf16 v[122:125], v[158:161], v[182:185], v[122:125]
	v_mfma_f32_16x16x32_bf16 v[110:113], v[150:153], v[190:193], v[110:113]
	v_mfma_f32_16x16x32_bf16 v[106:109], v[158:161], v[190:193], v[106:109]
	v_mfma_f32_16x16x32_bf16 v[94:97], v[150:153], v[198:201], v[94:97]
	v_mfma_f32_16x16x32_bf16 v[90:93], v[158:161], v[198:201], v[90:93]
	v_mfma_f32_16x16x32_bf16 v[78:81], v[150:153], v[206:209], v[78:81]
	v_mfma_f32_16x16x32_bf16 v[74:77], v[158:161], v[206:209], v[74:77]
	v_mfma_f32_16x16x32_bf16 v[126:129], v[154:157], v[186:189], v[126:129]
	v_mfma_f32_16x16x32_bf16 v[122:125], v[162:165], v[186:189], v[122:125]
	v_mfma_f32_16x16x32_bf16 v[110:113], v[154:157], v[194:197], v[110:113]
	v_mfma_f32_16x16x32_bf16 v[106:109], v[162:165], v[194:197], v[106:109]
	v_mfma_f32_16x16x32_bf16 v[94:97], v[154:157], v[202:205], v[94:97]
	v_mfma_f32_16x16x32_bf16 v[90:93], v[162:165], v[202:205], v[90:93]
	v_mfma_f32_16x16x32_bf16 v[78:81], v[154:157], v[210:213], v[78:81]
	v_mfma_f32_16x16x32_bf16 v[74:77], v[162:165], v[210:213], v[74:77]
	v_mfma_f32_16x16x32_bf16 v[118:121], v[166:169], v[182:185], v[118:121]
	v_mfma_f32_16x16x32_bf16 v[114:117], v[174:177], v[182:185], v[114:117]
	v_mfma_f32_16x16x32_bf16 v[102:105], v[166:169], v[190:193], v[102:105]
	v_mfma_f32_16x16x32_bf16 v[98:101], v[174:177], v[190:193], v[98:101]
	v_mfma_f32_16x16x32_bf16 v[86:89], v[166:169], v[198:201], v[86:89]
	v_mfma_f32_16x16x32_bf16 v[82:85], v[174:177], v[198:201], v[82:85]
	v_mfma_f32_16x16x32_bf16 v[70:73], v[166:169], v[206:209], v[70:73]
	v_mfma_f32_16x16x32_bf16 v[66:69], v[174:177], v[206:209], v[66:69]
	v_mfma_f32_16x16x32_bf16 v[118:121], v[170:173], v[186:189], v[118:121]
	v_mfma_f32_16x16x32_bf16 v[114:117], v[178:181], v[186:189], v[114:117]
	v_mfma_f32_16x16x32_bf16 v[102:105], v[170:173], v[194:197], v[102:105]
	v_mfma_f32_16x16x32_bf16 v[98:101], v[178:181], v[194:197], v[98:101]
	v_mfma_f32_16x16x32_bf16 v[86:89], v[170:173], v[202:205], v[86:89]
	v_mfma_f32_16x16x32_bf16 v[82:85], v[178:181], v[202:205], v[82:85]
	v_mfma_f32_16x16x32_bf16 v[70:73], v[170:173], v[210:213], v[70:73]
	v_mfma_f32_16x16x32_bf16 v[66:69], v[178:181], v[210:213], v[66:69]
	s_barrier
	s_mov_b32 m0, s72
	v_lshl_add_u64 v[144:145], v[144:145], 0, s[4:5]
	ds_read_b128 v[182:185], v149 offset:49152
	ds_read_b128 v[186:189], v149 offset:50176
	ds_read_b128 v[190:193], v149 offset:51200
	ds_read_b128 v[194:197], v149 offset:52224
	ds_read_b128 v[198:201], v149 offset:53248
	ds_read_b128 v[202:205], v149 offset:54272
	ds_read_b128 v[206:209], v149 offset:55296
	ds_read_b128 v[210:213], v149 offset:56320
	global_load_lds_dwordx4 v[144:145], off
	s_add_i32 m0, s72, 0x2000
	s_add_u32 s22, s26, 0x18080
	v_lshl_add_u64 v[144:145], v[214:215], 0, s[4:5]
	s_addc_u32 s23, s27, 0
	s_add_i32 s26, s71, s30
	global_load_lds_dwordx4 v[144:145], off
	v_lshl_add_u64 v[144:145], s[22:23], 0, v[134:135]
	s_mov_b32 m0, s26
	s_nop 0
	global_load_lds_dwordx4 v[144:145], off
	v_lshl_add_u64 v[144:145], s[22:23], 0, v[130:131]
	s_add_i32 m0, s26, 0x2000
	s_nop 0
	global_load_lds_dwordx4 v[144:145], off
	v_lshl_add_u64 v[144:145], v[216:217], 0, s[4:5]
	s_mov_b32 m0, s59
	s_nop 0
	global_load_lds_dwordx4 v[144:145], off
	v_lshl_add_u64 v[144:145], v[218:219], 0, s[4:5]
	s_mov_b32 m0, s60
	s_nop 0
	global_load_lds_dwordx4 v[144:145], off
	s_waitcnt vmcnt(8)
	s_waitcnt lgkmcnt(0)
	s_barrier
	v_mfma_f32_16x16x32_bf16 v[62:65], v[150:153], v[182:185], v[62:65]
	v_mfma_f32_16x16x32_bf16 v[58:61], v[158:161], v[182:185], v[58:61]
	v_mfma_f32_16x16x32_bf16 v[46:49], v[150:153], v[190:193], v[46:49]
	v_mfma_f32_16x16x32_bf16 v[42:45], v[158:161], v[190:193], v[42:45]
	v_mfma_f32_16x16x32_bf16 v[30:33], v[150:153], v[198:201], v[30:33]
	v_mfma_f32_16x16x32_bf16 v[26:29], v[158:161], v[198:201], v[26:29]
	v_mfma_f32_16x16x32_bf16 v[14:17], v[150:153], v[206:209], v[14:17]
	v_mfma_f32_16x16x32_bf16 v[10:13], v[158:161], v[206:209], v[10:13]
	v_mfma_f32_16x16x32_bf16 v[62:65], v[154:157], v[186:189], v[62:65]
	v_mfma_f32_16x16x32_bf16 v[58:61], v[162:165], v[186:189], v[58:61]
	v_mfma_f32_16x16x32_bf16 v[46:49], v[154:157], v[194:197], v[46:49]
	v_mfma_f32_16x16x32_bf16 v[42:45], v[162:165], v[194:197], v[42:45]
	v_mfma_f32_16x16x32_bf16 v[30:33], v[154:157], v[202:205], v[30:33]
	v_mfma_f32_16x16x32_bf16 v[26:29], v[162:165], v[202:205], v[26:29]
	v_mfma_f32_16x16x32_bf16 v[14:17], v[154:157], v[210:213], v[14:17]
	v_mfma_f32_16x16x32_bf16 v[10:13], v[162:165], v[210:213], v[10:13]
	v_mfma_f32_16x16x32_bf16 v[54:57], v[166:169], v[182:185], v[54:57]
	v_mfma_f32_16x16x32_bf16 v[50:53], v[174:177], v[182:185], v[50:53]
	v_mfma_f32_16x16x32_bf16 v[38:41], v[166:169], v[190:193], v[38:41]
	v_mfma_f32_16x16x32_bf16 v[34:37], v[174:177], v[190:193], v[34:37]
	v_mfma_f32_16x16x32_bf16 v[22:25], v[166:169], v[198:201], v[22:25]
	v_mfma_f32_16x16x32_bf16 v[18:21], v[174:177], v[198:201], v[18:21]
	v_mfma_f32_16x16x32_bf16 v[6:9], v[166:169], v[206:209], v[6:9]
	v_mfma_f32_16x16x32_bf16 v[2:5], v[174:177], v[206:209], v[2:5]
	v_mfma_f32_16x16x32_bf16 v[54:57], v[170:173], v[186:189], v[54:57]
	v_mfma_f32_16x16x32_bf16 v[50:53], v[178:181], v[186:189], v[50:53]
	v_mfma_f32_16x16x32_bf16 v[38:41], v[170:173], v[194:197], v[38:41]
	v_mfma_f32_16x16x32_bf16 v[34:37], v[178:181], v[194:197], v[34:37]
	v_mfma_f32_16x16x32_bf16 v[22:25], v[170:173], v[202:205], v[22:25]
	v_mfma_f32_16x16x32_bf16 v[18:21], v[178:181], v[202:205], v[18:21]
	v_mfma_f32_16x16x32_bf16 v[6:9], v[170:173], v[210:213], v[6:9]
	v_mfma_f32_16x16x32_bf16 v[2:5], v[178:181], v[210:213], v[2:5]
	s_barrier
	s_add_u32 s75, s75, 0x100
	s_addc_u32 s76, s76, 0
	s_cmp_ge_i32 s77, s57
	s_mov_b64 s[22:23], s[24:25]
	s_mov_b32 s26, s77
	s_cbranch_scc0 .LBB0_468

.LBB0_599:
	v_add_u32_e32 v142, s74, v199
	v_add_u32_e32 v162, s75, v199
	ds_read_b128 v[130:133], v142
	ds_read_b128 v[134:137], v142 offset:1024
	ds_read_b128 v[138:141], v142 offset:2048
	ds_read_b128 v[142:145], v142 offset:3072
	ds_read_b128 v[146:149], v162
	ds_read_b128 v[150:153], v162 offset:1024
	ds_read_b128 v[174:177], v162 offset:2048
	ds_read_b128 v[178:181], v162 offset:3072
	s_add_i32 s31, s52, 2
	s_add_u32 s50, s34, 0x3ff000
	s_addc_u32 s51, s35, 0
	s_cmp_eq_u32 s71, s52
	s_cselect_b32 s56, s26, s50
	s_cselect_b32 s57, s27, s51
	s_cselect_b32 s54, s28, s23
	s_cselect_b32 s55, s29, s25
	s_add_u32 s52, s56, 0x400000
	s_addc_u32 s53, s57, 0
	v_lshl_add_u64 v[218:219], s[34:35], 0, v[164:165]
	s_add_i32 m0, s59, 0xc000
	ds_read_b128 v[182:185], v200
	ds_read_b128 v[186:189], v200 offset:1024
	ds_read_b128 v[190:193], v200 offset:2048
	ds_read_b128 v[194:197], v200 offset:3072
	ds_read_b128 v[202:205], v200 offset:4096
	ds_read_b128 v[206:209], v200 offset:5120
	ds_read_b128 v[210:213], v200 offset:6144
	ds_read_b128 v[214:217], v200 offset:7168
	global_load_lds_dwordx4 v[218:219], off
	v_lshl_add_u64 v[218:219], s[34:35], 0, v[166:167]
	s_add_i32 m0, s59, 0xe000
	s_nop 0
	global_load_lds_dwordx4 v[218:219], off
	s_waitcnt vmcnt(8)
	s_waitcnt lgkmcnt(0)
	s_barrier
	v_mfma_f32_16x16x32_bf16 v[118:121], v[130:133], v[182:185], v[118:121]
	v_mfma_f32_16x16x32_bf16 v[122:125], v[138:141], v[182:185], v[122:125]
	v_mfma_f32_16x16x32_bf16 v[110:113], v[130:133], v[190:193], v[110:113]
	v_mfma_f32_16x16x32_bf16 v[106:109], v[138:141], v[190:193], v[106:109]
	v_mfma_f32_16x16x32_bf16 v[94:97], v[130:133], v[202:205], v[94:97]
	v_mfma_f32_16x16x32_bf16 v[90:93], v[138:141], v[202:205], v[90:93]
	v_mfma_f32_16x16x32_bf16 v[78:81], v[130:133], v[210:213], v[78:81]
	v_mfma_f32_16x16x32_bf16 v[74:77], v[138:141], v[210:213], v[74:77]
	v_mfma_f32_16x16x32_bf16 v[118:121], v[134:137], v[186:189], v[118:121]
	v_mfma_f32_16x16x32_bf16 v[122:125], v[142:145], v[186:189], v[122:125]
	v_mfma_f32_16x16x32_bf16 v[110:113], v[134:137], v[194:197], v[110:113]
	v_mfma_f32_16x16x32_bf16 v[106:109], v[142:145], v[194:197], v[106:109]
	v_mfma_f32_16x16x32_bf16 v[94:97], v[134:137], v[206:209], v[94:97]
	v_mfma_f32_16x16x32_bf16 v[90:93], v[142:145], v[206:209], v[90:93]
	v_mfma_f32_16x16x32_bf16 v[78:81], v[134:137], v[214:217], v[78:81]
	v_mfma_f32_16x16x32_bf16 v[74:77], v[142:145], v[214:217], v[74:77]
	v_mfma_f32_16x16x32_bf16 v[126:129], v[146:149], v[182:185], v[126:129]
	v_mfma_f32_16x16x32_bf16 v[114:117], v[174:177], v[182:185], v[114:117]
	v_mfma_f32_16x16x32_bf16 v[102:105], v[146:149], v[190:193], v[102:105]
	v_mfma_f32_16x16x32_bf16 v[98:101], v[174:177], v[190:193], v[98:101]
	v_mfma_f32_16x16x32_bf16 v[86:89], v[146:149], v[202:205], v[86:89]
	v_mfma_f32_16x16x32_bf16 v[82:85], v[174:177], v[202:205], v[82:85]
	v_mfma_f32_16x16x32_bf16 v[70:73], v[146:149], v[210:213], v[70:73]
	v_mfma_f32_16x16x32_bf16 v[66:69], v[174:177], v[210:213], v[66:69]
	v_mfma_f32_16x16x32_bf16 v[126:129], v[150:153], v[186:189], v[126:129]
	v_mfma_f32_16x16x32_bf16 v[114:117], v[178:181], v[186:189], v[114:117]
	v_mfma_f32_16x16x32_bf16 v[102:105], v[150:153], v[194:197], v[102:105]
	v_mfma_f32_16x16x32_bf16 v[98:101], v[178:181], v[194:197], v[98:101]
	v_mfma_f32_16x16x32_bf16 v[86:89], v[150:153], v[206:209], v[86:89]
	v_mfma_f32_16x16x32_bf16 v[82:85], v[178:181], v[206:209], v[82:85]
	v_mfma_f32_16x16x32_bf16 v[70:73], v[150:153], v[214:217], v[70:73]
	v_mfma_f32_16x16x32_bf16 v[66:69], v[178:181], v[214:217], v[66:69]
	s_barrier
	s_add_i32 s50, s74, s41
	v_lshl_add_u64 v[218:219], s[54:55], 0, v[156:157]
	s_mov_b32 m0, s50
	ds_read_b128 v[182:185], v200 offset:16384
	ds_read_b128 v[186:189], v200 offset:17408
	ds_read_b128 v[190:193], v200 offset:18432
	ds_read_b128 v[194:197], v200 offset:19456
	ds_read_b128 v[202:205], v200 offset:20480
	ds_read_b128 v[206:209], v200 offset:21504
	ds_read_b128 v[210:213], v200 offset:22528
	ds_read_b128 v[214:217], v200 offset:23552
	global_load_lds_dwordx4 v[218:219], off
	s_add_i32 m0, s50, 0x2000
	s_add_u32 s50, s54, 0x20000
	v_lshl_add_u64 v[220:221], s[54:55], 0, v[160:161]
	s_addc_u32 s51, s55, 0
	s_add_i32 s78, s75, s41
	global_load_lds_dwordx4 v[220:221], off
	v_lshl_add_u64 v[222:223], s[50:51], 0, v[156:157]
	s_mov_b32 m0, s78
	s_nop 0
	global_load_lds_dwordx4 v[222:223], off
	v_lshl_add_u64 v[222:223], s[50:51], 0, v[160:161]
	s_add_i32 m0, s78, 0x2000
	s_nop 0
	global_load_lds_dwordx4 v[222:223], off
	v_lshl_add_u64 v[222:223], s[56:57], 0, v[154:155]
	s_mov_b32 m0, s59
	s_nop 0
	global_load_lds_dwordx4 v[222:223], off
	v_lshl_add_u64 v[222:223], s[56:57], 0, v[158:159]
	s_mov_b32 m0, s60
	s_nop 0
	global_load_lds_dwordx4 v[222:223], off
	s_waitcnt vmcnt(8)
	s_waitcnt lgkmcnt(0)
	s_barrier
	v_mfma_f32_16x16x32_bf16 v[62:65], v[130:133], v[182:185], v[62:65]
	v_mfma_f32_16x16x32_bf16 v[58:61], v[138:141], v[182:185], v[58:61]
	v_mfma_f32_16x16x32_bf16 v[46:49], v[130:133], v[190:193], v[46:49]
	v_mfma_f32_16x16x32_bf16 v[42:45], v[138:141], v[190:193], v[42:45]
	v_mfma_f32_16x16x32_bf16 v[30:33], v[130:133], v[202:205], v[30:33]
	v_mfma_f32_16x16x32_bf16 v[26:29], v[138:141], v[202:205], v[26:29]
	v_mfma_f32_16x16x32_bf16 v[14:17], v[130:133], v[210:213], v[14:17]
	v_mfma_f32_16x16x32_bf16 v[10:13], v[138:141], v[210:213], v[10:13]
	v_mfma_f32_16x16x32_bf16 v[62:65], v[134:137], v[186:189], v[62:65]
	v_mfma_f32_16x16x32_bf16 v[58:61], v[142:145], v[186:189], v[58:61]
	v_mfma_f32_16x16x32_bf16 v[46:49], v[134:137], v[194:197], v[46:49]
	v_mfma_f32_16x16x32_bf16 v[42:45], v[142:145], v[194:197], v[42:45]
	v_mfma_f32_16x16x32_bf16 v[30:33], v[134:137], v[206:209], v[30:33]
	v_mfma_f32_16x16x32_bf16 v[26:29], v[142:145], v[206:209], v[26:29]
	v_mfma_f32_16x16x32_bf16 v[14:17], v[134:137], v[214:217], v[14:17]
	v_mfma_f32_16x16x32_bf16 v[10:13], v[142:145], v[214:217], v[10:13]
	v_mfma_f32_16x16x32_bf16 v[54:57], v[146:149], v[182:185], v[54:57]
	v_mfma_f32_16x16x32_bf16 v[50:53], v[174:177], v[182:185], v[50:53]
	v_mfma_f32_16x16x32_bf16 v[38:41], v[146:149], v[190:193], v[38:41]
	v_mfma_f32_16x16x32_bf16 v[34:37], v[174:177], v[190:193], v[34:37]
	v_mfma_f32_16x16x32_bf16 v[22:25], v[146:149], v[202:205], v[22:25]
	v_mfma_f32_16x16x32_bf16 v[18:21], v[174:177], v[202:205], v[18:21]
	v_mfma_f32_16x16x32_bf16 v[6:9], v[146:149], v[210:213], v[6:9]
	v_mfma_f32_16x16x32_bf16 v[2:5], v[174:177], v[210:213], v[2:5]
	v_mfma_f32_16x16x32_bf16 v[54:57], v[150:153], v[186:189], v[54:57]
	v_mfma_f32_16x16x32_bf16 v[50:53], v[178:181], v[186:189], v[50:53]
	v_mfma_f32_16x16x32_bf16 v[38:41], v[150:153], v[194:197], v[38:41]
	v_mfma_f32_16x16x32_bf16 v[34:37], v[178:181], v[194:197], v[34:37]
	v_mfma_f32_16x16x32_bf16 v[22:25], v[150:153], v[206:209], v[22:25]
	v_mfma_f32_16x16x32_bf16 v[18:21], v[178:181], v[206:209], v[18:21]
	v_mfma_f32_16x16x32_bf16 v[6:9], v[150:153], v[214:217], v[6:9]
	v_mfma_f32_16x16x32_bf16 v[2:5], v[178:181], v[214:217], v[2:5]
	s_barrier
	s_add_i32 s78, 0, 0x18000
	s_add_i32 s79, 0, 0x1c000
	v_add_u32_e32 v142, s78, v199
	v_add_u32_e32 v162, s79, v199
	ds_read_b128 v[130:133], v142
	ds_read_b128 v[134:137], v142 offset:1024
	ds_read_b128 v[138:141], v142 offset:2048
	ds_read_b128 v[142:145], v142 offset:3072
	ds_read_b128 v[146:149], v162
	ds_read_b128 v[150:153], v162 offset:1024
	ds_read_b128 v[174:177], v162 offset:2048
	ds_read_b128 v[178:181], v162 offset:3072
	s_add_u32 s50, s56, 0x1000
	s_addc_u32 s51, s57, 0
	s_mov_b32 m0, s61
	v_lshl_add_u64 v[222:223], s[50:51], 0, v[154:155]
	ds_read_b128 v[182:185], v200 offset:32768
	ds_read_b128 v[186:189], v200 offset:33792
	ds_read_b128 v[190:193], v200 offset:34816
	ds_read_b128 v[194:197], v200 offset:35840
	ds_read_b128 v[202:205], v200 offset:36864
	ds_read_b128 v[206:209], v200 offset:37888
	ds_read_b128 v[210:213], v200 offset:38912
	ds_read_b128 v[214:217], v200 offset:39936
	global_load_lds_dwordx4 v[222:223], off
	v_lshl_add_u64 v[222:223], s[50:51], 0, v[158:159]
	s_mov_b32 m0, s62
	s_nop 0
	global_load_lds_dwordx4 v[222:223], off
	s_waitcnt vmcnt(8)
	s_waitcnt lgkmcnt(0)
	s_barrier
	v_mfma_f32_16x16x32_bf16 v[118:121], v[130:133], v[182:185], v[118:121]
	v_mfma_f32_16x16x32_bf16 v[122:125], v[138:141], v[182:185], v[122:125]
	v_mfma_f32_16x16x32_bf16 v[110:113], v[130:133], v[190:193], v[110:113]
	v_mfma_f32_16x16x32_bf16 v[106:109], v[138:141], v[190:193], v[106:109]
	v_mfma_f32_16x16x32_bf16 v[94:97], v[130:133], v[202:205], v[94:97]
	v_mfma_f32_16x16x32_bf16 v[90:93], v[138:141], v[202:205], v[90:93]
	v_mfma_f32_16x16x32_bf16 v[78:81], v[130:133], v[210:213], v[78:81]
	v_mfma_f32_16x16x32_bf16 v[74:77], v[138:141], v[210:213], v[74:77]
	v_mfma_f32_16x16x32_bf16 v[118:121], v[134:137], v[186:189], v[118:121]
	v_mfma_f32_16x16x32_bf16 v[122:125], v[142:145], v[186:189], v[122:125]
	v_mfma_f32_16x16x32_bf16 v[110:113], v[134:137], v[194:197], v[110:113]
	v_mfma_f32_16x16x32_bf16 v[106:109], v[142:145], v[194:197], v[106:109]
	v_mfma_f32_16x16x32_bf16 v[94:97], v[134:137], v[206:209], v[94:97]
	v_mfma_f32_16x16x32_bf16 v[90:93], v[142:145], v[206:209], v[90:93]
	v_mfma_f32_16x16x32_bf16 v[78:81], v[134:137], v[214:217], v[78:81]
	v_mfma_f32_16x16x32_bf16 v[74:77], v[142:145], v[214:217], v[74:77]
	v_mfma_f32_16x16x32_bf16 v[126:129], v[146:149], v[182:185], v[126:129]
	v_mfma_f32_16x16x32_bf16 v[114:117], v[174:177], v[182:185], v[114:117]
	v_mfma_f32_16x16x32_bf16 v[102:105], v[146:149], v[190:193], v[102:105]
	v_mfma_f32_16x16x32_bf16 v[98:101], v[174:177], v[190:193], v[98:101]
	v_mfma_f32_16x16x32_bf16 v[86:89], v[146:149], v[202:205], v[86:89]
	v_mfma_f32_16x16x32_bf16 v[82:85], v[174:177], v[202:205], v[82:85]
	v_mfma_f32_16x16x32_bf16 v[70:73], v[146:149], v[210:213], v[70:73]
	v_mfma_f32_16x16x32_bf16 v[66:69], v[174:177], v[210:213], v[66:69]
	v_mfma_f32_16x16x32_bf16 v[126:129], v[150:153], v[186:189], v[126:129]
	v_mfma_f32_16x16x32_bf16 v[114:117], v[178:181], v[186:189], v[114:117]
	v_mfma_f32_16x16x32_bf16 v[102:105], v[150:153], v[194:197], v[102:105]
	v_mfma_f32_16x16x32_bf16 v[98:101], v[178:181], v[194:197], v[98:101]
	v_mfma_f32_16x16x32_bf16 v[86:89], v[150:153], v[206:209], v[86:89]
	v_mfma_f32_16x16x32_bf16 v[82:85], v[178:181], v[206:209], v[82:85]
	v_mfma_f32_16x16x32_bf16 v[70:73], v[150:153], v[214:217], v[70:73]
	v_mfma_f32_16x16x32_bf16 v[66:69], v[178:181], v[214:217], v[66:69]
	s_barrier
	s_add_i32 s50, s78, s41
	v_lshl_add_u64 v[218:219], v[218:219], 0, s[14:15]
	s_mov_b32 m0, s50
	ds_read_b128 v[182:185], v200 offset:49152
	ds_read_b128 v[186:189], v200 offset:50176
	ds_read_b128 v[190:193], v200 offset:51200
	ds_read_b128 v[194:197], v200 offset:52224
	ds_read_b128 v[202:205], v200 offset:53248
	ds_read_b128 v[206:209], v200 offset:54272
	ds_read_b128 v[210:213], v200 offset:55296
	ds_read_b128 v[214:217], v200 offset:56320
	global_load_lds_dwordx4 v[218:219], off
	s_add_i32 m0, s50, 0x2000
	s_add_u32 s50, s54, 0x20080
	v_lshl_add_u64 v[218:219], v[220:221], 0, s[14:15]
	s_addc_u32 s51, s55, 0
	s_add_i32 s54, s79, s41
	global_load_lds_dwordx4 v[218:219], off
	v_lshl_add_u64 v[218:219], s[50:51], 0, v[156:157]
	s_mov_b32 m0, s54
	s_nop 0
	global_load_lds_dwordx4 v[218:219], off
	v_lshl_add_u64 v[218:219], s[50:51], 0, v[160:161]
	s_add_i32 m0, s54, 0x2000
	s_nop 0
	global_load_lds_dwordx4 v[218:219], off
	v_lshl_add_u64 v[218:219], s[52:53], 0, v[154:155]
	s_mov_b32 m0, s69
	s_nop 0
	global_load_lds_dwordx4 v[218:219], off
	v_lshl_add_u64 v[218:219], s[52:53], 0, v[158:159]
	s_mov_b32 m0, s70
	s_nop 0
	global_load_lds_dwordx4 v[218:219], off
	s_waitcnt vmcnt(8)
	s_waitcnt lgkmcnt(0)
	s_barrier
	v_mfma_f32_16x16x32_bf16 v[62:65], v[130:133], v[182:185], v[62:65]
	v_mfma_f32_16x16x32_bf16 v[58:61], v[138:141], v[182:185], v[58:61]
	v_mfma_f32_16x16x32_bf16 v[46:49], v[130:133], v[190:193], v[46:49]
	v_mfma_f32_16x16x32_bf16 v[42:45], v[138:141], v[190:193], v[42:45]
	v_mfma_f32_16x16x32_bf16 v[30:33], v[130:133], v[202:205], v[30:33]
	v_mfma_f32_16x16x32_bf16 v[26:29], v[138:141], v[202:205], v[26:29]
	v_mfma_f32_16x16x32_bf16 v[14:17], v[130:133], v[210:213], v[14:17]
	v_mfma_f32_16x16x32_bf16 v[10:13], v[138:141], v[210:213], v[10:13]
	v_mfma_f32_16x16x32_bf16 v[62:65], v[134:137], v[186:189], v[62:65]
	v_mfma_f32_16x16x32_bf16 v[58:61], v[142:145], v[186:189], v[58:61]
	v_mfma_f32_16x16x32_bf16 v[46:49], v[134:137], v[194:197], v[46:49]
	v_mfma_f32_16x16x32_bf16 v[42:45], v[142:145], v[194:197], v[42:45]
	v_mfma_f32_16x16x32_bf16 v[30:33], v[134:137], v[206:209], v[30:33]
	v_mfma_f32_16x16x32_bf16 v[26:29], v[142:145], v[206:209], v[26:29]
	v_mfma_f32_16x16x32_bf16 v[14:17], v[134:137], v[214:217], v[14:17]
	v_mfma_f32_16x16x32_bf16 v[10:13], v[142:145], v[214:217], v[10:13]
	v_mfma_f32_16x16x32_bf16 v[54:57], v[146:149], v[182:185], v[54:57]
	v_mfma_f32_16x16x32_bf16 v[50:53], v[174:177], v[182:185], v[50:53]
	v_mfma_f32_16x16x32_bf16 v[38:41], v[146:149], v[190:193], v[38:41]
	v_mfma_f32_16x16x32_bf16 v[34:37], v[174:177], v[190:193], v[34:37]
	v_mfma_f32_16x16x32_bf16 v[22:25], v[146:149], v[202:205], v[22:25]
	v_mfma_f32_16x16x32_bf16 v[18:21], v[174:177], v[202:205], v[18:21]
	v_mfma_f32_16x16x32_bf16 v[6:9], v[146:149], v[210:213], v[6:9]
	v_mfma_f32_16x16x32_bf16 v[2:5], v[174:177], v[210:213], v[2:5]
	v_mfma_f32_16x16x32_bf16 v[54:57], v[150:153], v[186:189], v[54:57]
	v_mfma_f32_16x16x32_bf16 v[50:53], v[178:181], v[186:189], v[50:53]
	v_mfma_f32_16x16x32_bf16 v[38:41], v[150:153], v[194:197], v[38:41]
	v_mfma_f32_16x16x32_bf16 v[34:37], v[178:181], v[194:197], v[34:37]
	v_mfma_f32_16x16x32_bf16 v[22:25], v[150:153], v[206:209], v[22:25]
	v_mfma_f32_16x16x32_bf16 v[18:21], v[178:181], v[206:209], v[18:21]
	v_mfma_f32_16x16x32_bf16 v[6:9], v[150:153], v[214:217], v[6:9]
	v_mfma_f32_16x16x32_bf16 v[2:5], v[178:181], v[214:217], v[2:5]
	s_barrier
	s_add_u32 s23, s23, 0x100
	s_addc_u32 s25, s25, 0
	s_add_u32 s34, s34, 0x800000
	s_addc_u32 s35, s35, 0
	s_cmp_ge_i32 s31, s67
	s_mov_b32 s52, s31
	s_cbranch_scc0 .LBB0_599

.LBB0_740:
	v_add_u32_e32 v144, s88, v188
	v_add_u32_e32 v160, s89, v188
	ds_read_b128 v[132:135], v144
	ds_read_b128 v[136:139], v144 offset:1024
	ds_read_b128 v[140:143], v144 offset:2048
	ds_read_b128 v[144:147], v144 offset:3072
	ds_read_b128 v[148:151], v160
	ds_read_b128 v[152:155], v160 offset:1024
	ds_read_b128 v[156:159], v160 offset:2048
	ds_read_b128 v[184:187], v160 offset:3072
	s_add_i32 s92, s55, 2
	s_add_u32 s50, s60, 0x3fc000
	s_addc_u32 s51, s61, 0
	s_cmp_eq_u32 s87, s55
	s_cselect_b32 s70, s64, s50
	s_cselect_b32 s71, s65, s51
	s_cselect_b32 s69, s67, s53
	s_cselect_b32 s68, s66, s13
	s_add_u32 s62, s70, 0x400000
	s_addc_u32 s63, s71, 0
	v_lshl_add_u64 v[160:161], s[60:61], 0, v[176:177]
	s_add_i32 m0, s77, 0xc000
	ds_read_b128 v[192:195], v189
	ds_read_b128 v[196:199], v189 offset:1024
	ds_read_b128 v[200:203], v189 offset:2048
	ds_read_b128 v[204:207], v189 offset:3072
	ds_read_b128 v[208:211], v189 offset:4096
	ds_read_b128 v[212:215], v189 offset:5120
	ds_read_b128 v[216:219], v189 offset:6144
	ds_read_b128 v[220:223], v189 offset:7168
	global_load_lds_dwordx4 v[160:161], off
	v_lshl_add_u64 v[160:161], s[60:61], 0, v[178:179]
	s_add_i32 m0, s77, 0xe000
	s_nop 0
	global_load_lds_dwordx4 v[160:161], off
	s_waitcnt vmcnt(8)
	s_waitcnt lgkmcnt(0)
	s_barrier
	v_mfma_f32_16x16x32_bf16 v[30:33], v[132:135], v[192:195], v[30:33]
	v_mfma_f32_16x16x32_bf16 v[26:29], v[140:143], v[192:195], v[26:29]
	v_mfma_f32_16x16x32_bf16 v[86:89], v[132:135], v[200:203], v[86:89]
	v_mfma_f32_16x16x32_bf16 v[66:69], v[140:143], v[200:203], v[66:69]
	v_mfma_f32_16x16x32_bf16 v[94:97], v[132:135], v[208:211], v[94:97]
	v_mfma_f32_16x16x32_bf16 v[82:85], v[140:143], v[208:211], v[82:85]
	v_mfma_f32_16x16x32_bf16 v[90:93], v[132:135], v[216:219], v[90:93]
	v_mfma_f32_16x16x32_bf16 v[78:81], v[140:143], v[216:219], v[78:81]
	v_mfma_f32_16x16x32_bf16 v[30:33], v[136:139], v[196:199], v[30:33]
	v_mfma_f32_16x16x32_bf16 v[26:29], v[144:147], v[196:199], v[26:29]
	v_mfma_f32_16x16x32_bf16 v[86:89], v[136:139], v[204:207], v[86:89]
	v_mfma_f32_16x16x32_bf16 v[66:69], v[144:147], v[204:207], v[66:69]
	v_mfma_f32_16x16x32_bf16 v[94:97], v[136:139], v[212:215], v[94:97]
	v_mfma_f32_16x16x32_bf16 v[82:85], v[144:147], v[212:215], v[82:85]
	v_mfma_f32_16x16x32_bf16 v[90:93], v[136:139], v[220:223], v[90:93]
	v_mfma_f32_16x16x32_bf16 v[78:81], v[144:147], v[220:223], v[78:81]
	v_mfma_f32_16x16x32_bf16 v[50:53], v[148:151], v[192:195], v[50:53]
	v_mfma_f32_16x16x32_bf16 v[42:45], v[156:159], v[192:195], v[42:45]
	v_mfma_f32_16x16x32_bf16 v[14:17], v[148:151], v[200:203], v[14:17]
	v_mfma_f32_16x16x32_bf16 v[2:5], v[156:159], v[200:203], v[2:5]
	v_mfma_f32_16x16x32_bf16 v[22:25], v[148:151], v[208:211], v[22:25]
	v_mfma_f32_16x16x32_bf16 v[10:13], v[156:159], v[208:211], v[10:13]
	v_mfma_f32_16x16x32_bf16 v[18:21], v[148:151], v[216:219], v[18:21]
	v_mfma_f32_16x16x32_bf16 v[6:9], v[156:159], v[216:219], v[6:9]
	v_mfma_f32_16x16x32_bf16 v[50:53], v[152:155], v[196:199], v[50:53]
	v_mfma_f32_16x16x32_bf16 v[42:45], v[184:187], v[196:199], v[42:45]
	v_mfma_f32_16x16x32_bf16 v[14:17], v[152:155], v[204:207], v[14:17]
	v_mfma_f32_16x16x32_bf16 v[2:5], v[184:187], v[204:207], v[2:5]
	v_mfma_f32_16x16x32_bf16 v[22:25], v[152:155], v[212:215], v[22:25]
	v_mfma_f32_16x16x32_bf16 v[10:13], v[184:187], v[212:215], v[10:13]
	v_mfma_f32_16x16x32_bf16 v[18:21], v[152:155], v[220:223], v[18:21]
	v_mfma_f32_16x16x32_bf16 v[6:9], v[184:187], v[220:223], v[6:9]
	s_barrier
	s_add_i32 s50, s88, s76
	v_lshl_add_u64 v[160:161], s[68:69], 0, v[164:165]
	s_mov_b32 m0, s50
	ds_read_b128 v[192:195], v189 offset:16384
	ds_read_b128 v[196:199], v189 offset:17408
	ds_read_b128 v[200:203], v189 offset:18432
	ds_read_b128 v[204:207], v189 offset:19456
	ds_read_b128 v[208:211], v189 offset:20480
	ds_read_b128 v[212:215], v189 offset:21504
	ds_read_b128 v[216:219], v189 offset:22528
	ds_read_b128 v[220:223], v189 offset:23552
	global_load_lds_dwordx4 v[160:161], off
	s_add_i32 m0, s50, 0x2000
	s_add_u32 s50, s68, 0x10000
	v_lshl_add_u64 v[224:225], s[68:69], 0, v[168:169]
	s_addc_u32 s51, s69, 0
	s_add_i32 s55, s89, s76
	global_load_lds_dwordx4 v[224:225], off
	v_lshl_add_u64 v[226:227], s[50:51], 0, v[164:165]
	s_mov_b32 m0, s55
	s_nop 0
	global_load_lds_dwordx4 v[226:227], off
	v_lshl_add_u64 v[226:227], s[50:51], 0, v[168:169]
	s_add_i32 m0, s55, 0x2000
	s_nop 0
	global_load_lds_dwordx4 v[226:227], off
	v_lshl_add_u64 v[226:227], s[70:71], 0, v[162:163]
	s_mov_b32 m0, s77
	s_nop 0
	global_load_lds_dwordx4 v[226:227], off
	v_lshl_add_u64 v[226:227], s[70:71], 0, v[166:167]
	s_mov_b32 m0, s78
	s_nop 0
	global_load_lds_dwordx4 v[226:227], off
	s_waitcnt vmcnt(8)
	s_waitcnt lgkmcnt(0)
	s_barrier
	v_mfma_f32_16x16x32_bf16 v[118:121], v[132:135], v[192:195], v[118:121]
	v_mfma_f32_16x16x32_bf16 v[102:105], v[140:143], v[192:195], v[102:105]
	v_mfma_f32_16x16x32_bf16 v[114:117], v[132:135], v[200:203], v[114:117]
	v_mfma_f32_16x16x32_bf16 v[98:101], v[140:143], v[200:203], v[98:101]
	v_mfma_f32_16x16x32_bf16 v[126:129], v[132:135], v[208:211], v[126:129]
	v_mfma_f32_16x16x32_bf16 v[110:113], v[140:143], v[208:211], v[110:113]
	v_mfma_f32_16x16x32_bf16 v[122:125], v[132:135], v[216:219], v[122:125]
	v_mfma_f32_16x16x32_bf16 v[106:109], v[140:143], v[216:219], v[106:109]
	v_mfma_f32_16x16x32_bf16 v[118:121], v[136:139], v[196:199], v[118:121]
	v_mfma_f32_16x16x32_bf16 v[102:105], v[144:147], v[196:199], v[102:105]
	v_mfma_f32_16x16x32_bf16 v[114:117], v[136:139], v[204:207], v[114:117]
	v_mfma_f32_16x16x32_bf16 v[98:101], v[144:147], v[204:207], v[98:101]
	v_mfma_f32_16x16x32_bf16 v[126:129], v[136:139], v[212:215], v[126:129]
	v_mfma_f32_16x16x32_bf16 v[110:113], v[144:147], v[212:215], v[110:113]
	v_mfma_f32_16x16x32_bf16 v[122:125], v[136:139], v[220:223], v[122:125]
	v_mfma_f32_16x16x32_bf16 v[106:109], v[144:147], v[220:223], v[106:109]
	v_mfma_f32_16x16x32_bf16 v[62:65], v[148:151], v[192:195], v[62:65]
	v_mfma_f32_16x16x32_bf16 v[38:41], v[156:159], v[192:195], v[38:41]
	v_mfma_f32_16x16x32_bf16 v[58:61], v[148:151], v[200:203], v[58:61]
	v_mfma_f32_16x16x32_bf16 v[34:37], v[156:159], v[200:203], v[34:37]
	v_mfma_f32_16x16x32_bf16 v[74:77], v[148:151], v[208:211], v[74:77]
	v_mfma_f32_16x16x32_bf16 v[54:57], v[156:159], v[208:211], v[54:57]
	v_mfma_f32_16x16x32_bf16 v[70:73], v[148:151], v[216:219], v[70:73]
	v_mfma_f32_16x16x32_bf16 v[46:49], v[156:159], v[216:219], v[46:49]
	v_mfma_f32_16x16x32_bf16 v[62:65], v[152:155], v[196:199], v[62:65]
	v_mfma_f32_16x16x32_bf16 v[38:41], v[184:187], v[196:199], v[38:41]
	v_mfma_f32_16x16x32_bf16 v[58:61], v[152:155], v[204:207], v[58:61]
	v_mfma_f32_16x16x32_bf16 v[34:37], v[184:187], v[204:207], v[34:37]
	v_mfma_f32_16x16x32_bf16 v[74:77], v[152:155], v[212:215], v[74:77]
	v_mfma_f32_16x16x32_bf16 v[54:57], v[184:187], v[212:215], v[54:57]
	v_mfma_f32_16x16x32_bf16 v[70:73], v[152:155], v[220:223], v[70:73]
	v_mfma_f32_16x16x32_bf16 v[46:49], v[184:187], v[220:223], v[46:49]
	s_barrier
	s_add_i32 s55, 0, 0x18000
	s_add_i32 s93, 0, 0x1c000
	v_add_u32_e32 v144, s55, v188
	v_add_u32_e32 v184, s93, v188
	ds_read_b128 v[132:135], v144
	ds_read_b128 v[136:139], v144 offset:1024
	ds_read_b128 v[140:143], v144 offset:2048
	ds_read_b128 v[144:147], v144 offset:3072
	ds_read_b128 v[148:151], v184
	ds_read_b128 v[152:155], v184 offset:1024
	ds_read_b128 v[156:159], v184 offset:2048
	ds_read_b128 v[184:187], v184 offset:3072
	s_add_u32 s50, s70, 0x4000
	s_addc_u32 s51, s71, 0
	s_mov_b32 m0, s79
	v_lshl_add_u64 v[226:227], s[50:51], 0, v[162:163]
	ds_read_b128 v[192:195], v189 offset:32768
	ds_read_b128 v[196:199], v189 offset:33792
	ds_read_b128 v[200:203], v189 offset:34816
	ds_read_b128 v[204:207], v189 offset:35840
	ds_read_b128 v[208:211], v189 offset:36864
	ds_read_b128 v[212:215], v189 offset:37888
	ds_read_b128 v[216:219], v189 offset:38912
	ds_read_b128 v[220:223], v189 offset:39936
	global_load_lds_dwordx4 v[226:227], off
	v_lshl_add_u64 v[226:227], s[50:51], 0, v[166:167]
	s_mov_b32 m0, s80
	s_nop 0
	global_load_lds_dwordx4 v[226:227], off
	s_waitcnt vmcnt(8)
	s_waitcnt lgkmcnt(0)
	s_barrier
	v_mfma_f32_16x16x32_bf16 v[30:33], v[132:135], v[192:195], v[30:33]
	v_mfma_f32_16x16x32_bf16 v[26:29], v[140:143], v[192:195], v[26:29]
	v_mfma_f32_16x16x32_bf16 v[86:89], v[132:135], v[200:203], v[86:89]
	v_mfma_f32_16x16x32_bf16 v[66:69], v[140:143], v[200:203], v[66:69]
	v_mfma_f32_16x16x32_bf16 v[94:97], v[132:135], v[208:211], v[94:97]
	v_mfma_f32_16x16x32_bf16 v[82:85], v[140:143], v[208:211], v[82:85]
	v_mfma_f32_16x16x32_bf16 v[90:93], v[132:135], v[216:219], v[90:93]
	v_mfma_f32_16x16x32_bf16 v[78:81], v[140:143], v[216:219], v[78:81]
	v_mfma_f32_16x16x32_bf16 v[30:33], v[136:139], v[196:199], v[30:33]
	v_mfma_f32_16x16x32_bf16 v[26:29], v[144:147], v[196:199], v[26:29]
	v_mfma_f32_16x16x32_bf16 v[86:89], v[136:139], v[204:207], v[86:89]
	v_mfma_f32_16x16x32_bf16 v[66:69], v[144:147], v[204:207], v[66:69]
	v_mfma_f32_16x16x32_bf16 v[94:97], v[136:139], v[212:215], v[94:97]
	v_mfma_f32_16x16x32_bf16 v[82:85], v[144:147], v[212:215], v[82:85]
	v_mfma_f32_16x16x32_bf16 v[90:93], v[136:139], v[220:223], v[90:93]
	v_mfma_f32_16x16x32_bf16 v[78:81], v[144:147], v[220:223], v[78:81]
	v_mfma_f32_16x16x32_bf16 v[50:53], v[148:151], v[192:195], v[50:53]
	v_mfma_f32_16x16x32_bf16 v[42:45], v[156:159], v[192:195], v[42:45]
	v_mfma_f32_16x16x32_bf16 v[14:17], v[148:151], v[200:203], v[14:17]
	v_mfma_f32_16x16x32_bf16 v[2:5], v[156:159], v[200:203], v[2:5]
	v_mfma_f32_16x16x32_bf16 v[22:25], v[148:151], v[208:211], v[22:25]
	v_mfma_f32_16x16x32_bf16 v[10:13], v[156:159], v[208:211], v[10:13]
	v_mfma_f32_16x16x32_bf16 v[18:21], v[148:151], v[216:219], v[18:21]
	v_mfma_f32_16x16x32_bf16 v[6:9], v[156:159], v[216:219], v[6:9]
	v_mfma_f32_16x16x32_bf16 v[50:53], v[152:155], v[196:199], v[50:53]
	v_mfma_f32_16x16x32_bf16 v[42:45], v[184:187], v[196:199], v[42:45]
	v_mfma_f32_16x16x32_bf16 v[14:17], v[152:155], v[204:207], v[14:17]
	v_mfma_f32_16x16x32_bf16 v[2:5], v[184:187], v[204:207], v[2:5]
	v_mfma_f32_16x16x32_bf16 v[22:25], v[152:155], v[212:215], v[22:25]
	v_mfma_f32_16x16x32_bf16 v[10:13], v[184:187], v[212:215], v[10:13]
	v_mfma_f32_16x16x32_bf16 v[18:21], v[152:155], v[220:223], v[18:21]
	v_mfma_f32_16x16x32_bf16 v[6:9], v[184:187], v[220:223], v[6:9]
	s_barrier
	s_add_i32 s50, s55, s76
	v_lshl_add_u64 v[160:161], v[160:161], 0, s[14:15]
	s_mov_b32 m0, s50
	ds_read_b128 v[192:195], v189 offset:49152
	ds_read_b128 v[196:199], v189 offset:50176
	ds_read_b128 v[200:203], v189 offset:51200
	ds_read_b128 v[204:207], v189 offset:52224
	ds_read_b128 v[208:211], v189 offset:53248
	ds_read_b128 v[212:215], v189 offset:54272
	ds_read_b128 v[216:219], v189 offset:55296
	ds_read_b128 v[220:223], v189 offset:56320
	global_load_lds_dwordx4 v[160:161], off
	s_add_i32 m0, s50, 0x2000
	s_add_u32 s50, s68, 0x10080
	v_lshl_add_u64 v[160:161], v[224:225], 0, s[14:15]
	s_addc_u32 s51, s69, 0
	s_add_i32 s55, s93, s76
	global_load_lds_dwordx4 v[160:161], off
	v_lshl_add_u64 v[160:161], s[50:51], 0, v[164:165]
	s_mov_b32 m0, s55
	s_nop 0
	global_load_lds_dwordx4 v[160:161], off
	v_lshl_add_u64 v[160:161], s[50:51], 0, v[168:169]
	s_add_i32 m0, s55, 0x2000
	s_nop 0
	global_load_lds_dwordx4 v[160:161], off
	v_lshl_add_u64 v[160:161], s[62:63], 0, v[162:163]
	s_mov_b32 m0, s84
	s_nop 0
	global_load_lds_dwordx4 v[160:161], off
	v_lshl_add_u64 v[160:161], s[62:63], 0, v[166:167]
	s_mov_b32 m0, s85
	s_nop 0
	global_load_lds_dwordx4 v[160:161], off
	s_waitcnt vmcnt(8)
	s_waitcnt lgkmcnt(0)
	s_barrier
	v_mfma_f32_16x16x32_bf16 v[118:121], v[132:135], v[192:195], v[118:121]
	v_mfma_f32_16x16x32_bf16 v[102:105], v[140:143], v[192:195], v[102:105]
	v_mfma_f32_16x16x32_bf16 v[114:117], v[132:135], v[200:203], v[114:117]
	v_mfma_f32_16x16x32_bf16 v[98:101], v[140:143], v[200:203], v[98:101]
	v_mfma_f32_16x16x32_bf16 v[126:129], v[132:135], v[208:211], v[126:129]
	v_mfma_f32_16x16x32_bf16 v[110:113], v[140:143], v[208:211], v[110:113]
	v_mfma_f32_16x16x32_bf16 v[122:125], v[132:135], v[216:219], v[122:125]
	v_mfma_f32_16x16x32_bf16 v[106:109], v[140:143], v[216:219], v[106:109]
	v_mfma_f32_16x16x32_bf16 v[118:121], v[136:139], v[196:199], v[118:121]
	v_mfma_f32_16x16x32_bf16 v[102:105], v[144:147], v[196:199], v[102:105]
	v_mfma_f32_16x16x32_bf16 v[114:117], v[136:139], v[204:207], v[114:117]
	v_mfma_f32_16x16x32_bf16 v[98:101], v[144:147], v[204:207], v[98:101]
	v_mfma_f32_16x16x32_bf16 v[126:129], v[136:139], v[212:215], v[126:129]
	v_mfma_f32_16x16x32_bf16 v[110:113], v[144:147], v[212:215], v[110:113]
	v_mfma_f32_16x16x32_bf16 v[122:125], v[136:139], v[220:223], v[122:125]
	v_mfma_f32_16x16x32_bf16 v[106:109], v[144:147], v[220:223], v[106:109]
	v_mfma_f32_16x16x32_bf16 v[62:65], v[148:151], v[192:195], v[62:65]
	v_mfma_f32_16x16x32_bf16 v[38:41], v[156:159], v[192:195], v[38:41]
	v_mfma_f32_16x16x32_bf16 v[58:61], v[148:151], v[200:203], v[58:61]
	v_mfma_f32_16x16x32_bf16 v[34:37], v[156:159], v[200:203], v[34:37]
	v_mfma_f32_16x16x32_bf16 v[74:77], v[148:151], v[208:211], v[74:77]
	v_mfma_f32_16x16x32_bf16 v[54:57], v[156:159], v[208:211], v[54:57]
	v_mfma_f32_16x16x32_bf16 v[70:73], v[148:151], v[216:219], v[70:73]
	v_mfma_f32_16x16x32_bf16 v[46:49], v[156:159], v[216:219], v[46:49]
	v_mfma_f32_16x16x32_bf16 v[62:65], v[152:155], v[196:199], v[62:65]
	v_mfma_f32_16x16x32_bf16 v[38:41], v[184:187], v[196:199], v[38:41]
	v_mfma_f32_16x16x32_bf16 v[58:61], v[152:155], v[204:207], v[58:61]
	v_mfma_f32_16x16x32_bf16 v[34:37], v[184:187], v[204:207], v[34:37]
	v_mfma_f32_16x16x32_bf16 v[74:77], v[152:155], v[212:215], v[74:77]
	v_mfma_f32_16x16x32_bf16 v[54:57], v[184:187], v[212:215], v[54:57]
	v_mfma_f32_16x16x32_bf16 v[70:73], v[152:155], v[220:223], v[70:73]
	v_mfma_f32_16x16x32_bf16 v[46:49], v[184:187], v[220:223], v[46:49]
	s_barrier
	s_add_u32 s13, s13, 0x100
	s_addc_u32 s53, s53, 0
	s_add_u32 s60, s60, 0x800000
	s_addc_u32 s61, s61, 0
	s_cmp_ge_i32 s92, s83
	s_cbranch_scc0 .LBB0_738

.LBB0_872:
	v_add_u32_e32 v162, s73, v140
	v_add_u32_e32 v178, s74, v140
	ds_read_b128 v[150:153], v162
	ds_read_b128 v[154:157], v162 offset:1024
	ds_read_b128 v[158:161], v162 offset:2048
	ds_read_b128 v[162:165], v162 offset:3072
	ds_read_b128 v[166:169], v178
	ds_read_b128 v[170:173], v178 offset:1024
	ds_read_b128 v[174:177], v178 offset:2048
	ds_read_b128 v[178:181], v178 offset:3072
	s_add_i32 s77, s52, 2
	s_add_u32 s50, s34, 0xfffc0080
	s_addc_u32 s51, s35, -1
	s_cmp_eq_u32 s70, s52
	s_cselect_b32 s52, s30, s21
	s_cselect_b32 s55, s29, s51
	s_cselect_b32 s54, s28, s50
	s_cselect_b32 s53, s31, s23
	v_lshl_add_u64 v[214:215], s[34:35], 0, v[132:133]
	s_add_i32 m0, s60, 0xc000
	ds_read_b128 v[182:185], v149
	ds_read_b128 v[186:189], v149 offset:1024
	ds_read_b128 v[190:193], v149 offset:2048
	ds_read_b128 v[194:197], v149 offset:3072
	ds_read_b128 v[198:201], v149 offset:4096
	ds_read_b128 v[202:205], v149 offset:5120
	ds_read_b128 v[206:209], v149 offset:6144
	ds_read_b128 v[210:213], v149 offset:7168
	global_load_lds_dwordx4 v[214:215], off
	v_lshl_add_u64 v[214:215], s[34:35], 0, v[134:135]
	s_add_i32 m0, s60, 0xe000
	s_nop 0
	global_load_lds_dwordx4 v[214:215], off
	s_waitcnt vmcnt(8)
	s_waitcnt lgkmcnt(0)
	s_barrier
	v_mfma_f32_16x16x32_bf16 v[78:81], v[150:153], v[182:185], v[78:81]
	v_mfma_f32_16x16x32_bf16 v[14:17], v[158:161], v[182:185], v[14:17]
	v_mfma_f32_16x16x32_bf16 v[66:69], v[150:153], v[190:193], v[66:69]
	v_mfma_f32_16x16x32_bf16 v[2:5], v[158:161], v[190:193], v[2:5]
	v_mfma_f32_16x16x32_bf16 v[70:73], v[150:153], v[198:201], v[70:73]
	v_mfma_f32_16x16x32_bf16 v[6:9], v[158:161], v[198:201], v[6:9]
	v_mfma_f32_16x16x32_bf16 v[74:77], v[150:153], v[206:209], v[74:77]
	v_mfma_f32_16x16x32_bf16 v[10:13], v[158:161], v[206:209], v[10:13]
	v_mfma_f32_16x16x32_bf16 v[78:81], v[154:157], v[186:189], v[78:81]
	v_mfma_f32_16x16x32_bf16 v[14:17], v[162:165], v[186:189], v[14:17]
	v_mfma_f32_16x16x32_bf16 v[66:69], v[154:157], v[194:197], v[66:69]
	v_mfma_f32_16x16x32_bf16 v[2:5], v[162:165], v[194:197], v[2:5]
	v_mfma_f32_16x16x32_bf16 v[70:73], v[154:157], v[202:205], v[70:73]
	v_mfma_f32_16x16x32_bf16 v[6:9], v[162:165], v[202:205], v[6:9]
	v_mfma_f32_16x16x32_bf16 v[74:77], v[154:157], v[210:213], v[74:77]
	v_mfma_f32_16x16x32_bf16 v[10:13], v[162:165], v[210:213], v[10:13]
	v_mfma_f32_16x16x32_bf16 v[98:101], v[166:169], v[182:185], v[98:101]
	v_mfma_f32_16x16x32_bf16 v[34:37], v[174:177], v[182:185], v[34:37]
	v_mfma_f32_16x16x32_bf16 v[82:85], v[166:169], v[190:193], v[82:85]
	v_mfma_f32_16x16x32_bf16 v[18:21], v[174:177], v[190:193], v[18:21]
	v_mfma_f32_16x16x32_bf16 v[86:89], v[166:169], v[198:201], v[86:89]
	v_mfma_f32_16x16x32_bf16 v[22:25], v[174:177], v[198:201], v[22:25]
	v_mfma_f32_16x16x32_bf16 v[94:97], v[166:169], v[206:209], v[94:97]
	v_mfma_f32_16x16x32_bf16 v[30:33], v[174:177], v[206:209], v[30:33]
	v_mfma_f32_16x16x32_bf16 v[98:101], v[170:173], v[186:189], v[98:101]
	v_mfma_f32_16x16x32_bf16 v[34:37], v[178:181], v[186:189], v[34:37]
	v_mfma_f32_16x16x32_bf16 v[82:85], v[170:173], v[194:197], v[82:85]
	v_mfma_f32_16x16x32_bf16 v[18:21], v[178:181], v[194:197], v[18:21]
	v_mfma_f32_16x16x32_bf16 v[86:89], v[170:173], v[202:205], v[86:89]
	v_mfma_f32_16x16x32_bf16 v[22:25], v[178:181], v[202:205], v[22:25]
	v_mfma_f32_16x16x32_bf16 v[94:97], v[170:173], v[210:213], v[94:97]
	v_mfma_f32_16x16x32_bf16 v[30:33], v[178:181], v[210:213], v[30:33]
	s_barrier
	s_add_i32 s50, s73, s15
	v_lshl_add_u64 v[214:215], s[52:53], 0, v[228:229]
	s_mov_b32 m0, s50
	ds_read_b128 v[182:185], v149 offset:16384
	ds_read_b128 v[186:189], v149 offset:17408
	ds_read_b128 v[190:193], v149 offset:18432
	ds_read_b128 v[194:197], v149 offset:19456
	ds_read_b128 v[198:201], v149 offset:20480
	ds_read_b128 v[202:205], v149 offset:21504
	ds_read_b128 v[206:209], v149 offset:22528
	ds_read_b128 v[210:213], v149 offset:23552
	global_load_lds_dwordx4 v[214:215], off
	s_add_i32 m0, s50, 0x2000
	s_add_u32 s50, s52, 0x40000
	v_lshl_add_u64 v[216:217], s[52:53], 0, v[232:233]
	s_addc_u32 s51, s53, 0
	s_add_i32 s78, s74, s15
	global_load_lds_dwordx4 v[216:217], off
	v_lshl_add_u64 v[218:219], s[50:51], 0, v[228:229]
	s_mov_b32 m0, s78
	v_lshl_add_u64 v[220:221], s[54:55], 0, v[230:231]
	global_load_lds_dwordx4 v[218:219], off
	v_lshl_add_u64 v[218:219], s[50:51], 0, v[232:233]
	s_add_i32 m0, s78, 0x2000
	s_nop 0
	global_load_lds_dwordx4 v[218:219], off
	v_lshl_add_u64 v[218:219], s[54:55], 0, v[226:227]
	s_mov_b32 m0, s60
	s_nop 0
	global_load_lds_dwordx4 v[218:219], off
	s_mov_b32 m0, s61
	s_nop 0
	global_load_lds_dwordx4 v[220:221], off
	s_waitcnt vmcnt(8)
	s_waitcnt lgkmcnt(0)
	s_barrier
	v_mfma_f32_16x16x32_bf16 v[90:93], v[150:153], v[182:185], v[90:93]
	v_mfma_f32_16x16x32_bf16 v[26:29], v[158:161], v[182:185], v[26:29]
	v_mfma_f32_16x16x32_bf16 v[102:105], v[150:153], v[190:193], v[102:105]
	v_mfma_f32_16x16x32_bf16 v[38:41], v[158:161], v[190:193], v[38:41]
	v_mfma_f32_16x16x32_bf16 v[106:109], v[150:153], v[198:201], v[106:109]
	v_mfma_f32_16x16x32_bf16 v[42:45], v[158:161], v[198:201], v[42:45]
	v_mfma_f32_16x16x32_bf16 v[110:113], v[150:153], v[206:209], v[110:113]
	v_mfma_f32_16x16x32_bf16 v[46:49], v[158:161], v[206:209], v[46:49]
	v_mfma_f32_16x16x32_bf16 v[90:93], v[154:157], v[186:189], v[90:93]
	v_mfma_f32_16x16x32_bf16 v[26:29], v[162:165], v[186:189], v[26:29]
	v_mfma_f32_16x16x32_bf16 v[102:105], v[154:157], v[194:197], v[102:105]
	v_mfma_f32_16x16x32_bf16 v[38:41], v[162:165], v[194:197], v[38:41]
	v_mfma_f32_16x16x32_bf16 v[106:109], v[154:157], v[202:205], v[106:109]
	v_mfma_f32_16x16x32_bf16 v[42:45], v[162:165], v[202:205], v[42:45]
	v_mfma_f32_16x16x32_bf16 v[110:113], v[154:157], v[210:213], v[110:113]
	v_mfma_f32_16x16x32_bf16 v[46:49], v[162:165], v[210:213], v[46:49]
	v_mfma_f32_16x16x32_bf16 v[114:117], v[166:169], v[182:185], v[114:117]
	v_mfma_f32_16x16x32_bf16 v[50:53], v[174:177], v[182:185], v[50:53]
	v_mfma_f32_16x16x32_bf16 v[118:121], v[166:169], v[190:193], v[118:121]
	v_mfma_f32_16x16x32_bf16 v[54:57], v[174:177], v[190:193], v[54:57]
	v_mfma_f32_16x16x32_bf16 v[122:125], v[166:169], v[198:201], v[122:125]
	v_mfma_f32_16x16x32_bf16 v[58:61], v[174:177], v[198:201], v[58:61]
	v_mfma_f32_16x16x32_bf16 v[126:129], v[166:169], v[206:209], v[126:129]
	v_mfma_f32_16x16x32_bf16 v[62:65], v[174:177], v[206:209], v[62:65]
	v_mfma_f32_16x16x32_bf16 v[114:117], v[170:173], v[186:189], v[114:117]
	v_mfma_f32_16x16x32_bf16 v[50:53], v[178:181], v[186:189], v[50:53]
	v_mfma_f32_16x16x32_bf16 v[118:121], v[170:173], v[194:197], v[118:121]
	v_mfma_f32_16x16x32_bf16 v[54:57], v[178:181], v[194:197], v[54:57]
	v_mfma_f32_16x16x32_bf16 v[122:125], v[170:173], v[202:205], v[122:125]
	v_mfma_f32_16x16x32_bf16 v[58:61], v[178:181], v[202:205], v[58:61]
	v_mfma_f32_16x16x32_bf16 v[126:129], v[170:173], v[210:213], v[126:129]
	v_mfma_f32_16x16x32_bf16 v[62:65], v[178:181], v[210:213], v[62:65]
	s_barrier
	s_add_i32 s78, 0, 0x18000
	s_add_i32 s79, 0, 0x1c000
	v_add_u32_e32 v162, s78, v140
	v_add_u32_e32 v178, s79, v140
	ds_read_b128 v[150:153], v162
	ds_read_b128 v[154:157], v162 offset:1024
	ds_read_b128 v[158:161], v162 offset:2048
	ds_read_b128 v[162:165], v162 offset:3072
	ds_read_b128 v[166:169], v178
	ds_read_b128 v[170:173], v178 offset:1024
	ds_read_b128 v[174:177], v178 offset:2048
	ds_read_b128 v[178:181], v178 offset:3072
	s_add_u32 s50, s54, 0x40000
	s_addc_u32 s51, s55, 0
	s_mov_b32 m0, s62
	v_lshl_add_u64 v[222:223], s[50:51], 0, v[226:227]
	ds_read_b128 v[182:185], v149 offset:32768
	ds_read_b128 v[186:189], v149 offset:33792
	ds_read_b128 v[190:193], v149 offset:34816
	ds_read_b128 v[194:197], v149 offset:35840
	ds_read_b128 v[198:201], v149 offset:36864
	ds_read_b128 v[202:205], v149 offset:37888
	ds_read_b128 v[206:209], v149 offset:38912
	ds_read_b128 v[210:213], v149 offset:39936
	global_load_lds_dwordx4 v[222:223], off
	v_lshl_add_u64 v[222:223], s[50:51], 0, v[230:231]
	s_mov_b32 m0, s63
	s_nop 0
	global_load_lds_dwordx4 v[222:223], off
	s_waitcnt vmcnt(8)
	s_waitcnt lgkmcnt(0)
	s_barrier
	v_mfma_f32_16x16x32_bf16 v[78:81], v[150:153], v[182:185], v[78:81]
	v_mfma_f32_16x16x32_bf16 v[14:17], v[158:161], v[182:185], v[14:17]
	v_mfma_f32_16x16x32_bf16 v[66:69], v[150:153], v[190:193], v[66:69]
	v_mfma_f32_16x16x32_bf16 v[2:5], v[158:161], v[190:193], v[2:5]
	v_mfma_f32_16x16x32_bf16 v[70:73], v[150:153], v[198:201], v[70:73]
	v_mfma_f32_16x16x32_bf16 v[6:9], v[158:161], v[198:201], v[6:9]
	v_mfma_f32_16x16x32_bf16 v[74:77], v[150:153], v[206:209], v[74:77]
	v_mfma_f32_16x16x32_bf16 v[10:13], v[158:161], v[206:209], v[10:13]
	v_mfma_f32_16x16x32_bf16 v[78:81], v[154:157], v[186:189], v[78:81]
	v_mfma_f32_16x16x32_bf16 v[14:17], v[162:165], v[186:189], v[14:17]
	v_mfma_f32_16x16x32_bf16 v[66:69], v[154:157], v[194:197], v[66:69]
	v_mfma_f32_16x16x32_bf16 v[2:5], v[162:165], v[194:197], v[2:5]
	v_mfma_f32_16x16x32_bf16 v[70:73], v[154:157], v[202:205], v[70:73]
	v_mfma_f32_16x16x32_bf16 v[6:9], v[162:165], v[202:205], v[6:9]
	v_mfma_f32_16x16x32_bf16 v[74:77], v[154:157], v[210:213], v[74:77]
	v_mfma_f32_16x16x32_bf16 v[10:13], v[162:165], v[210:213], v[10:13]
	v_mfma_f32_16x16x32_bf16 v[98:101], v[166:169], v[182:185], v[98:101]
	v_mfma_f32_16x16x32_bf16 v[34:37], v[174:177], v[182:185], v[34:37]
	v_mfma_f32_16x16x32_bf16 v[82:85], v[166:169], v[190:193], v[82:85]
	v_mfma_f32_16x16x32_bf16 v[18:21], v[174:177], v[190:193], v[18:21]
	v_mfma_f32_16x16x32_bf16 v[86:89], v[166:169], v[198:201], v[86:89]
	v_mfma_f32_16x16x32_bf16 v[22:25], v[174:177], v[198:201], v[22:25]
	v_mfma_f32_16x16x32_bf16 v[94:97], v[166:169], v[206:209], v[94:97]
	v_mfma_f32_16x16x32_bf16 v[30:33], v[174:177], v[206:209], v[30:33]
	v_mfma_f32_16x16x32_bf16 v[98:101], v[170:173], v[186:189], v[98:101]
	v_mfma_f32_16x16x32_bf16 v[34:37], v[178:181], v[186:189], v[34:37]
	v_mfma_f32_16x16x32_bf16 v[82:85], v[170:173], v[194:197], v[82:85]
	v_mfma_f32_16x16x32_bf16 v[18:21], v[178:181], v[194:197], v[18:21]
	v_mfma_f32_16x16x32_bf16 v[86:89], v[170:173], v[202:205], v[86:89]
	v_mfma_f32_16x16x32_bf16 v[22:25], v[178:181], v[202:205], v[22:25]
	v_mfma_f32_16x16x32_bf16 v[94:97], v[170:173], v[210:213], v[94:97]
	v_mfma_f32_16x16x32_bf16 v[30:33], v[178:181], v[210:213], v[30:33]
	s_barrier
	s_add_i32 s50, s78, s15
	v_lshl_add_u64 v[214:215], v[214:215], 0, s[8:9]
	s_mov_b32 m0, s50
	ds_read_b128 v[182:185], v149 offset:49152
	ds_read_b128 v[186:189], v149 offset:50176
	ds_read_b128 v[190:193], v149 offset:51200
	ds_read_b128 v[194:197], v149 offset:52224
	ds_read_b128 v[198:201], v149 offset:53248
	ds_read_b128 v[202:205], v149 offset:54272
	ds_read_b128 v[206:209], v149 offset:55296
	ds_read_b128 v[210:213], v149 offset:56320
	global_load_lds_dwordx4 v[214:215], off
	s_add_i32 m0, s50, 0x2000
	s_add_u32 s50, s52, 0x40080
	v_lshl_add_u64 v[214:215], v[216:217], 0, s[8:9]
	s_addc_u32 s51, s53, 0
	s_add_i32 s52, s79, s15
	global_load_lds_dwordx4 v[214:215], off
	v_lshl_add_u64 v[214:215], s[50:51], 0, v[228:229]
	s_mov_b32 m0, s52
	s_nop 0
	global_load_lds_dwordx4 v[214:215], off
	v_lshl_add_u64 v[214:215], s[50:51], 0, v[232:233]
	s_add_i32 m0, s52, 0x2000
	s_nop 0
	global_load_lds_dwordx4 v[214:215], off
	v_lshl_add_u64 v[214:215], v[218:219], 0, s[8:9]
	s_mov_b32 m0, s68
	s_nop 0
	global_load_lds_dwordx4 v[214:215], off
	v_lshl_add_u64 v[214:215], v[220:221], 0, s[8:9]
	s_mov_b32 m0, s69
	s_nop 0
	global_load_lds_dwordx4 v[214:215], off
	s_waitcnt vmcnt(8)
	s_waitcnt lgkmcnt(0)
	s_barrier
	v_mfma_f32_16x16x32_bf16 v[90:93], v[150:153], v[182:185], v[90:93]
	v_mfma_f32_16x16x32_bf16 v[26:29], v[158:161], v[182:185], v[26:29]
	v_mfma_f32_16x16x32_bf16 v[102:105], v[150:153], v[190:193], v[102:105]
	v_mfma_f32_16x16x32_bf16 v[38:41], v[158:161], v[190:193], v[38:41]
	v_mfma_f32_16x16x32_bf16 v[106:109], v[150:153], v[198:201], v[106:109]
	v_mfma_f32_16x16x32_bf16 v[42:45], v[158:161], v[198:201], v[42:45]
	v_mfma_f32_16x16x32_bf16 v[110:113], v[150:153], v[206:209], v[110:113]
	v_mfma_f32_16x16x32_bf16 v[46:49], v[158:161], v[206:209], v[46:49]
	v_mfma_f32_16x16x32_bf16 v[90:93], v[154:157], v[186:189], v[90:93]
	v_mfma_f32_16x16x32_bf16 v[26:29], v[162:165], v[186:189], v[26:29]
	v_mfma_f32_16x16x32_bf16 v[102:105], v[154:157], v[194:197], v[102:105]
	v_mfma_f32_16x16x32_bf16 v[38:41], v[162:165], v[194:197], v[38:41]
	v_mfma_f32_16x16x32_bf16 v[106:109], v[154:157], v[202:205], v[106:109]
	v_mfma_f32_16x16x32_bf16 v[42:45], v[162:165], v[202:205], v[42:45]
	v_mfma_f32_16x16x32_bf16 v[110:113], v[154:157], v[210:213], v[110:113]
	v_mfma_f32_16x16x32_bf16 v[46:49], v[162:165], v[210:213], v[46:49]
	v_mfma_f32_16x16x32_bf16 v[114:117], v[166:169], v[182:185], v[114:117]
	v_mfma_f32_16x16x32_bf16 v[50:53], v[174:177], v[182:185], v[50:53]
	v_mfma_f32_16x16x32_bf16 v[118:121], v[166:169], v[190:193], v[118:121]
	v_mfma_f32_16x16x32_bf16 v[54:57], v[174:177], v[190:193], v[54:57]
	v_mfma_f32_16x16x32_bf16 v[122:125], v[166:169], v[198:201], v[122:125]
	v_mfma_f32_16x16x32_bf16 v[58:61], v[174:177], v[198:201], v[58:61]
	v_mfma_f32_16x16x32_bf16 v[126:129], v[166:169], v[206:209], v[126:129]
	v_mfma_f32_16x16x32_bf16 v[62:65], v[174:177], v[206:209], v[62:65]
	v_mfma_f32_16x16x32_bf16 v[114:117], v[170:173], v[186:189], v[114:117]
	v_mfma_f32_16x16x32_bf16 v[50:53], v[178:181], v[186:189], v[50:53]
	v_mfma_f32_16x16x32_bf16 v[118:121], v[170:173], v[194:197], v[118:121]
	v_mfma_f32_16x16x32_bf16 v[54:57], v[178:181], v[194:197], v[54:57]
	v_mfma_f32_16x16x32_bf16 v[122:125], v[170:173], v[202:205], v[122:125]
	v_mfma_f32_16x16x32_bf16 v[58:61], v[178:181], v[202:205], v[58:61]
	v_mfma_f32_16x16x32_bf16 v[126:129], v[170:173], v[210:213], v[126:129]
	v_mfma_f32_16x16x32_bf16 v[62:65], v[178:181], v[210:213], v[62:65]
	s_barrier
	s_add_u32 s34, s34, 0x100
	s_addc_u32 s35, s35, 0
	s_add_u32 s21, s21, 0x100
	s_addc_u32 s23, s23, 0
	s_cmp_ge_i32 s77, s66
	s_mov_b32 s52, s77
	s_cbranch_scc0 .LBB0_872

.LBB0_1009:
	v_add_u32_e32 v0, s64, v187
	ds_read_b128 v[130:133], v0
	ds_read_b128 v[134:137], v0 offset:1024
	ds_read_b128 v[138:141], v0 offset:2048
	ds_read_b128 v[142:145], v0 offset:3072
	v_add_u32_e32 v0, s65, v187
	ds_read_b128 v[146:149], v0
	ds_read_b128 v[150:153], v0 offset:1024
	ds_read_b128 v[178:181], v0 offset:2048
	ds_read_b128 v[182:185], v0 offset:3072
	s_add_i32 s35, s42, 2
	s_add_u32 s43, s36, 0x3fc000
	s_addc_u32 s44, s37, 0
	s_cmp_eq_u32 s61, s42
	s_cselect_b32 s46, s28, s43
	s_cselect_b32 s47, s29, s44
	s_cselect_b32 s44, s30, s11
	s_cselect_b32 s45, s31, s27
	s_add_u32 s42, s46, 0x400000
	s_addc_u32 s43, s47, 0
	v_lshl_add_u64 v[0:1], s[36:37], 0, v[168:169]
	s_add_i32 m0, s51, 0xc000
	ds_read_b128 v[220:223], v215
	ds_read_b128 v[224:227], v215 offset:1024
	ds_read_b128 v[228:231], v215 offset:2048
	ds_read_b128 v[232:235], v215 offset:3072
	ds_read_b128 v[236:239], v215 offset:4096
	ds_read_b128 v[240:243], v215 offset:5120
	ds_read_b128 v[244:247], v215 offset:6144
	ds_read_b128 v[248:251], v215 offset:7168
	global_load_lds_dwordx4 v[0:1], off
	v_lshl_add_u64 v[0:1], s[36:37], 0, v[170:171]
	s_add_i32 m0, s51, 0xe000
	s_nop 0
	global_load_lds_dwordx4 v[0:1], off
	s_waitcnt vmcnt(8)
	s_waitcnt lgkmcnt(0)
	s_barrier
	v_mfma_f32_16x16x32_bf16 v[114:117], v[130:133], v[220:223], v[114:117]
	v_mfma_f32_16x16x32_bf16 v[118:121], v[138:141], v[220:223], v[118:121]
	v_mfma_f32_16x16x32_bf16 v[110:113], v[130:133], v[228:231], v[110:113]
	v_mfma_f32_16x16x32_bf16 v[102:105], v[138:141], v[228:231], v[102:105]
	v_mfma_f32_16x16x32_bf16 v[94:97], v[130:133], v[236:239], v[94:97]
	v_mfma_f32_16x16x32_bf16 v[86:89], v[138:141], v[236:239], v[86:89]
	v_mfma_f32_16x16x32_bf16 v[78:81], v[130:133], v[244:247], v[78:81]
	v_mfma_f32_16x16x32_bf16 v[70:73], v[138:141], v[244:247], v[70:73]
	v_mfma_f32_16x16x32_bf16 v[114:117], v[134:137], v[224:227], v[114:117]
	v_mfma_f32_16x16x32_bf16 v[118:121], v[142:145], v[224:227], v[118:121]
	v_mfma_f32_16x16x32_bf16 v[110:113], v[134:137], v[232:235], v[110:113]
	v_mfma_f32_16x16x32_bf16 v[102:105], v[142:145], v[232:235], v[102:105]
	v_mfma_f32_16x16x32_bf16 v[94:97], v[134:137], v[240:243], v[94:97]
	v_mfma_f32_16x16x32_bf16 v[86:89], v[142:145], v[240:243], v[86:89]
	v_mfma_f32_16x16x32_bf16 v[78:81], v[134:137], v[248:251], v[78:81]
	v_mfma_f32_16x16x32_bf16 v[70:73], v[142:145], v[248:251], v[70:73]
	v_mfma_f32_16x16x32_bf16 v[126:129], v[146:149], v[220:223], v[126:129]
	v_mfma_f32_16x16x32_bf16 v[122:125], v[178:181], v[220:223], v[122:125]
	v_mfma_f32_16x16x32_bf16 v[106:109], v[146:149], v[228:231], v[106:109]
	v_mfma_f32_16x16x32_bf16 v[98:101], v[178:181], v[228:231], v[98:101]
	v_mfma_f32_16x16x32_bf16 v[90:93], v[146:149], v[236:239], v[90:93]
	v_mfma_f32_16x16x32_bf16 v[82:85], v[178:181], v[236:239], v[82:85]
	v_mfma_f32_16x16x32_bf16 v[74:77], v[146:149], v[244:247], v[74:77]
	v_mfma_f32_16x16x32_bf16 v[66:69], v[178:181], v[244:247], v[66:69]
	v_mfma_f32_16x16x32_bf16 v[126:129], v[150:153], v[224:227], v[126:129]
	v_mfma_f32_16x16x32_bf16 v[122:125], v[182:185], v[224:227], v[122:125]
	v_mfma_f32_16x16x32_bf16 v[106:109], v[150:153], v[232:235], v[106:109]
	v_mfma_f32_16x16x32_bf16 v[98:101], v[182:185], v[232:235], v[98:101]
	v_mfma_f32_16x16x32_bf16 v[90:93], v[150:153], v[240:243], v[90:93]
	v_mfma_f32_16x16x32_bf16 v[82:85], v[182:185], v[240:243], v[82:85]
	v_mfma_f32_16x16x32_bf16 v[74:77], v[150:153], v[248:251], v[74:77]
	v_mfma_f32_16x16x32_bf16 v[66:69], v[182:185], v[248:251], v[66:69]
	s_barrier
	s_add_i32 s69, s64, s49
	v_lshl_add_u64 v[252:253], s[44:45], 0, v[156:157]
	s_mov_b32 m0, s69
	ds_read_b128 v[220:223], v215 offset:16384
	ds_read_b128 v[224:227], v215 offset:17408
	ds_read_b128 v[228:231], v215 offset:18432
	ds_read_b128 v[232:235], v215 offset:19456
	ds_read_b128 v[236:239], v215 offset:20480
	ds_read_b128 v[240:243], v215 offset:21504
	ds_read_b128 v[244:247], v215 offset:22528
	ds_read_b128 v[248:251], v215 offset:23552
	global_load_lds_dwordx4 v[252:253], off
	s_add_i32 m0, s69, 0x2000
	s_add_u32 s70, s44, 0xb0000
	v_lshl_add_u64 v[172:173], s[44:45], 0, v[160:161]
	s_addc_u32 s71, s45, 0
	s_add_i32 s69, s65, s49
	global_load_lds_dwordx4 v[172:173], off
	v_lshl_add_u64 v[0:1], s[70:71], 0, v[156:157]
	s_mov_b32 m0, s69
	s_nop 0
	global_load_lds_dwordx4 v[0:1], off
	v_lshl_add_u64 v[0:1], s[70:71], 0, v[160:161]
	s_add_i32 m0, s69, 0x2000
	s_nop 0
	global_load_lds_dwordx4 v[0:1], off
	v_lshl_add_u64 v[0:1], s[46:47], 0, v[154:155]
	s_mov_b32 m0, s51
	s_nop 0
	global_load_lds_dwordx4 v[0:1], off
	v_lshl_add_u64 v[0:1], s[46:47], 0, v[158:159]
	s_mov_b32 m0, s52
	s_nop 0
	global_load_lds_dwordx4 v[0:1], off
	s_waitcnt vmcnt(8)
	s_waitcnt lgkmcnt(0)
	s_barrier
	v_mfma_f32_16x16x32_bf16 v[50:53], v[130:133], v[220:223], v[50:53]
	v_mfma_f32_16x16x32_bf16 v[54:57], v[138:141], v[220:223], v[54:57]
	v_mfma_f32_16x16x32_bf16 v[46:49], v[130:133], v[228:231], v[46:49]
	v_mfma_f32_16x16x32_bf16 v[38:41], v[138:141], v[228:231], v[38:41]
	v_mfma_f32_16x16x32_bf16 v[30:33], v[130:133], v[236:239], v[30:33]
	v_mfma_f32_16x16x32_bf16 v[22:25], v[138:141], v[236:239], v[22:25]
	v_mfma_f32_16x16x32_bf16 v[14:17], v[130:133], v[244:247], v[14:17]
	v_mfma_f32_16x16x32_bf16 v[6:9], v[138:141], v[244:247], v[6:9]
	v_mfma_f32_16x16x32_bf16 v[50:53], v[134:137], v[224:227], v[50:53]
	v_mfma_f32_16x16x32_bf16 v[54:57], v[142:145], v[224:227], v[54:57]
	v_mfma_f32_16x16x32_bf16 v[46:49], v[134:137], v[232:235], v[46:49]
	v_mfma_f32_16x16x32_bf16 v[38:41], v[142:145], v[232:235], v[38:41]
	v_mfma_f32_16x16x32_bf16 v[30:33], v[134:137], v[240:243], v[30:33]
	v_mfma_f32_16x16x32_bf16 v[22:25], v[142:145], v[240:243], v[22:25]
	v_mfma_f32_16x16x32_bf16 v[14:17], v[134:137], v[248:251], v[14:17]
	v_mfma_f32_16x16x32_bf16 v[6:9], v[142:145], v[248:251], v[6:9]
	v_mfma_f32_16x16x32_bf16 v[62:65], v[146:149], v[220:223], v[62:65]
	v_mfma_f32_16x16x32_bf16 v[58:61], v[178:181], v[220:223], v[58:61]
	v_mfma_f32_16x16x32_bf16 v[42:45], v[146:149], v[228:231], v[42:45]
	v_mfma_f32_16x16x32_bf16 v[34:37], v[178:181], v[228:231], v[34:37]
	v_mfma_f32_16x16x32_bf16 v[26:29], v[146:149], v[236:239], v[26:29]
	v_mfma_f32_16x16x32_bf16 v[18:21], v[178:181], v[236:239], v[18:21]
	v_mfma_f32_16x16x32_bf16 v[10:13], v[146:149], v[244:247], v[10:13]
	v_mfma_f32_16x16x32_bf16 v[0:3], v[178:181], v[244:247], v[2:5]
	v_mfma_f32_16x16x32_bf16 v[62:65], v[150:153], v[224:227], v[62:65]
	v_mfma_f32_16x16x32_bf16 v[58:61], v[182:185], v[224:227], v[58:61]
	v_mfma_f32_16x16x32_bf16 v[42:45], v[150:153], v[232:235], v[42:45]
	v_mfma_f32_16x16x32_bf16 v[34:37], v[182:185], v[232:235], v[34:37]
	v_mfma_f32_16x16x32_bf16 v[26:29], v[150:153], v[240:243], v[26:29]
	v_mfma_f32_16x16x32_bf16 v[18:21], v[182:185], v[240:243], v[18:21]
	v_mfma_f32_16x16x32_bf16 v[10:13], v[150:153], v[248:251], v[10:13]
	v_mfma_f32_16x16x32_bf16 v[0:3], v[182:185], v[248:251], v[0:3]
	s_barrier
	s_add_i32 s69, 0, 0x18000
	v_add_u32_e32 v4, s69, v187
	s_add_i32 s70, 0, 0x1c000
	ds_read_b128 v[130:133], v4
	ds_read_b128 v[134:137], v4 offset:1024
	ds_read_b128 v[138:141], v4 offset:2048
	ds_read_b128 v[142:145], v4 offset:3072
	v_add_u32_e32 v4, s70, v187
	ds_read_b128 v[146:149], v4
	ds_read_b128 v[150:153], v4 offset:1024
	ds_read_b128 v[178:181], v4 offset:2048
	ds_read_b128 v[182:185], v4 offset:3072
	s_add_u32 s46, s46, 0x4000
	s_addc_u32 s47, s47, 0
	s_mov_b32 m0, s53
	v_lshl_add_u64 v[4:5], s[46:47], 0, v[154:155]
	ds_read_b128 v[220:223], v215 offset:32768
	ds_read_b128 v[224:227], v215 offset:33792
	ds_read_b128 v[228:231], v215 offset:34816
	ds_read_b128 v[232:235], v215 offset:35840
	ds_read_b128 v[236:239], v215 offset:36864
	ds_read_b128 v[240:243], v215 offset:37888
	ds_read_b128 v[244:247], v215 offset:38912
	ds_read_b128 v[248:251], v215 offset:39936
	global_load_lds_dwordx4 v[4:5], off
	v_lshl_add_u64 v[4:5], s[46:47], 0, v[158:159]
	s_mov_b32 m0, s54
	s_nop 0
	global_load_lds_dwordx4 v[4:5], off
	s_waitcnt vmcnt(8)
	s_waitcnt lgkmcnt(0)
	s_barrier
	v_mfma_f32_16x16x32_bf16 v[114:117], v[130:133], v[220:223], v[114:117]
	v_mfma_f32_16x16x32_bf16 v[118:121], v[138:141], v[220:223], v[118:121]
	v_mfma_f32_16x16x32_bf16 v[110:113], v[130:133], v[228:231], v[110:113]
	v_mfma_f32_16x16x32_bf16 v[102:105], v[138:141], v[228:231], v[102:105]
	v_mfma_f32_16x16x32_bf16 v[94:97], v[130:133], v[236:239], v[94:97]
	v_mfma_f32_16x16x32_bf16 v[86:89], v[138:141], v[236:239], v[86:89]
	v_mfma_f32_16x16x32_bf16 v[78:81], v[130:133], v[244:247], v[78:81]
	v_mfma_f32_16x16x32_bf16 v[70:73], v[138:141], v[244:247], v[70:73]
	v_mfma_f32_16x16x32_bf16 v[114:117], v[134:137], v[224:227], v[114:117]
	v_mfma_f32_16x16x32_bf16 v[118:121], v[142:145], v[224:227], v[118:121]
	v_mfma_f32_16x16x32_bf16 v[110:113], v[134:137], v[232:235], v[110:113]
	v_mfma_f32_16x16x32_bf16 v[102:105], v[142:145], v[232:235], v[102:105]
	v_mfma_f32_16x16x32_bf16 v[94:97], v[134:137], v[240:243], v[94:97]
	v_mfma_f32_16x16x32_bf16 v[86:89], v[142:145], v[240:243], v[86:89]
	v_mfma_f32_16x16x32_bf16 v[78:81], v[134:137], v[248:251], v[78:81]
	v_mfma_f32_16x16x32_bf16 v[70:73], v[142:145], v[248:251], v[70:73]
	v_mfma_f32_16x16x32_bf16 v[126:129], v[146:149], v[220:223], v[126:129]
	v_mfma_f32_16x16x32_bf16 v[122:125], v[178:181], v[220:223], v[122:125]
	v_mfma_f32_16x16x32_bf16 v[106:109], v[146:149], v[228:231], v[106:109]
	v_mfma_f32_16x16x32_bf16 v[98:101], v[178:181], v[228:231], v[98:101]
	v_mfma_f32_16x16x32_bf16 v[90:93], v[146:149], v[236:239], v[90:93]
	v_mfma_f32_16x16x32_bf16 v[82:85], v[178:181], v[236:239], v[82:85]
	v_mfma_f32_16x16x32_bf16 v[74:77], v[146:149], v[244:247], v[74:77]
	v_mfma_f32_16x16x32_bf16 v[66:69], v[178:181], v[244:247], v[66:69]
	v_mfma_f32_16x16x32_bf16 v[126:129], v[150:153], v[224:227], v[126:129]
	v_mfma_f32_16x16x32_bf16 v[122:125], v[182:185], v[224:227], v[122:125]
	v_mfma_f32_16x16x32_bf16 v[106:109], v[150:153], v[232:235], v[106:109]
	v_mfma_f32_16x16x32_bf16 v[98:101], v[182:185], v[232:235], v[98:101]
	v_mfma_f32_16x16x32_bf16 v[90:93], v[150:153], v[240:243], v[90:93]
	v_mfma_f32_16x16x32_bf16 v[82:85], v[182:185], v[240:243], v[82:85]
	v_mfma_f32_16x16x32_bf16 v[74:77], v[150:153], v[248:251], v[74:77]
	v_mfma_f32_16x16x32_bf16 v[66:69], v[182:185], v[248:251], v[66:69]
	s_barrier
	s_add_i32 s46, s69, s49
	v_lshl_add_u64 v[4:5], v[252:253], 0, s[18:19]
	s_mov_b32 m0, s46
	ds_read_b128 v[220:223], v215 offset:49152
	ds_read_b128 v[224:227], v215 offset:50176
	ds_read_b128 v[228:231], v215 offset:51200
	ds_read_b128 v[232:235], v215 offset:52224
	ds_read_b128 v[236:239], v215 offset:53248
	ds_read_b128 v[240:243], v215 offset:54272
	ds_read_b128 v[244:247], v215 offset:55296
	ds_read_b128 v[248:251], v215 offset:56320
	global_load_lds_dwordx4 v[4:5], off
	s_add_i32 m0, s46, 0x2000
	s_add_u32 s44, s44, 0xb0080
	v_lshl_add_u64 v[4:5], v[172:173], 0, s[18:19]
	s_addc_u32 s45, s45, 0
	s_add_i32 s46, s70, s49
	global_load_lds_dwordx4 v[4:5], off
	v_lshl_add_u64 v[4:5], s[44:45], 0, v[156:157]
	s_mov_b32 m0, s46
	s_nop 0
	global_load_lds_dwordx4 v[4:5], off
	v_lshl_add_u64 v[4:5], s[44:45], 0, v[160:161]
	s_add_i32 m0, s46, 0x2000
	s_nop 0
	global_load_lds_dwordx4 v[4:5], off
	v_lshl_add_u64 v[4:5], s[42:43], 0, v[154:155]
	s_mov_b32 m0, s59
	s_nop 0
	global_load_lds_dwordx4 v[4:5], off
	v_lshl_add_u64 v[4:5], s[42:43], 0, v[158:159]
	s_mov_b32 m0, s60
	s_nop 0
	global_load_lds_dwordx4 v[4:5], off
	s_waitcnt vmcnt(8)
	s_waitcnt lgkmcnt(0)
	s_barrier
	v_mfma_f32_16x16x32_bf16 v[50:53], v[130:133], v[220:223], v[50:53]
	v_mfma_f32_16x16x32_bf16 v[54:57], v[138:141], v[220:223], v[54:57]
	v_mfma_f32_16x16x32_bf16 v[46:49], v[130:133], v[228:231], v[46:49]
	v_mfma_f32_16x16x32_bf16 v[38:41], v[138:141], v[228:231], v[38:41]
	v_mfma_f32_16x16x32_bf16 v[30:33], v[130:133], v[236:239], v[30:33]
	v_mfma_f32_16x16x32_bf16 v[22:25], v[138:141], v[236:239], v[22:25]
	v_mfma_f32_16x16x32_bf16 v[14:17], v[130:133], v[244:247], v[14:17]
	v_mfma_f32_16x16x32_bf16 v[4:7], v[138:141], v[244:247], v[6:9]
	v_mfma_f32_16x16x32_bf16 v[50:53], v[134:137], v[224:227], v[50:53]
	v_mfma_f32_16x16x32_bf16 v[54:57], v[142:145], v[224:227], v[54:57]
	v_mfma_f32_16x16x32_bf16 v[46:49], v[134:137], v[232:235], v[46:49]
	v_mfma_f32_16x16x32_bf16 v[38:41], v[142:145], v[232:235], v[38:41]
	v_mfma_f32_16x16x32_bf16 v[30:33], v[134:137], v[240:243], v[30:33]
	v_mfma_f32_16x16x32_bf16 v[22:25], v[142:145], v[240:243], v[22:25]
	v_mfma_f32_16x16x32_bf16 v[14:17], v[134:137], v[248:251], v[14:17]
	v_mfma_f32_16x16x32_bf16 v[6:9], v[142:145], v[248:251], v[4:7]
	v_mfma_f32_16x16x32_bf16 v[62:65], v[146:149], v[220:223], v[62:65]
	v_mfma_f32_16x16x32_bf16 v[58:61], v[178:181], v[220:223], v[58:61]
	v_mfma_f32_16x16x32_bf16 v[42:45], v[146:149], v[228:231], v[42:45]
	v_mfma_f32_16x16x32_bf16 v[34:37], v[178:181], v[228:231], v[34:37]
	v_mfma_f32_16x16x32_bf16 v[26:29], v[146:149], v[236:239], v[26:29]
	v_mfma_f32_16x16x32_bf16 v[18:21], v[178:181], v[236:239], v[18:21]
	v_mfma_f32_16x16x32_bf16 v[10:13], v[146:149], v[244:247], v[10:13]
	v_mfma_f32_16x16x32_bf16 v[0:3], v[178:181], v[244:247], v[0:3]
	v_mfma_f32_16x16x32_bf16 v[62:65], v[150:153], v[224:227], v[62:65]
	v_mfma_f32_16x16x32_bf16 v[58:61], v[182:185], v[224:227], v[58:61]
	v_mfma_f32_16x16x32_bf16 v[42:45], v[150:153], v[232:235], v[42:45]
	v_mfma_f32_16x16x32_bf16 v[34:37], v[182:185], v[232:235], v[34:37]
	v_mfma_f32_16x16x32_bf16 v[26:29], v[150:153], v[240:243], v[26:29]
	v_mfma_f32_16x16x32_bf16 v[18:21], v[182:185], v[240:243], v[18:21]
	v_mfma_f32_16x16x32_bf16 v[10:13], v[150:153], v[248:251], v[10:13]
	v_mfma_f32_16x16x32_bf16 v[2:5], v[182:185], v[248:251], v[0:3]
	s_barrier
	s_add_u32 s11, s11, 0x100
	s_addc_u32 s27, s27, 0
	s_add_u32 s36, s36, 0x800000
	s_addc_u32 s37, s37, 0
	s_cmp_ge_i32 s35, s58
	s_mov_b32 s42, s35
	s_cbranch_scc0 .LBB0_1009
	v_mov_b64_e32 v[234:235], v[174:175]
	s_and_b64 vcc, exec, s[22:23]
	s_cbranch_vccnz .LBB0_980
	s_branch .LBB0_981
